# plus: residual epilogues (G2/G5/G7) issue their 16 residual loads up front with counted vmcnt waits
# speedup vs baseline: 1.0128x; 1.0089x over previous
; #define GAS __attribute__((address_space(1)))
; __device__ __forceinline__ v4u tr4(int a, v4u x) { return (v4u){bperm(a, x.x), bperm(a, x.y), bperm(a, x.z), bperm(a, x.w)}; }
; __device__ __forceinline__ v4u pack8(const f32x4& a, const f32x4& b) { return (v4u){pg8::cvt_pk_bf16(a[0], a[1]), pg8::cvt_pk_bf16(a[2], a[3]), pg8::cvt_pk_bf16(b[0], b[1]), pg8::cvt_pk_bf16(b[2], b[3])}; }
;     __device__ __forceinline__ bool operator()(AccT& acc, const Unit& u, int wr, int wc, int fr, int fq) const {
;     ...
;         const int row0 = u.pm * 256 + wr * 64 + t.tfr, col0 = u.pn * 256 + wc * 32 + 8 * t.tfq;
; #pragma unroll
;         for (int ai = 0; ai < 2; ++ai)
; #pragma unroll
;             for (int m = 0; m < 4; ++m) { const size_t off = (size_t)(row0 + ai * 128 + m * 16) * D + col0;
; #pragma unroll
;                 for (int bj = 0; bj < 2; ++bj) { const v4u r = tr4(t.push, *(const GAS v4u*)(src + off + bj * 128));
;                     const f32x4 y0 = (f32x4){bflo(r.x), bfhi(r.x), bflo(r.y), bfhi(r.y)} * ca + acc[ai][bj][m][0] * cb, y1 = (f32x4){bflo(r.z), bfhi(r.z), bflo(r.w), bfhi(r.w)} * ca + acc[ai][bj][m][1] * cb;
;                     *(GAS v4u*)(dst + off + bj * 128) = tr4(t.pull, pack8(y0, y1)); } }
.LBB0_242:
	s_mov_b32 s12, s41
	v_mov_b32_e32 v130, v1
	s_mov_b32 s13, s29
	v_mov_b32_e32 v131, v245
	s_lshl_b32 s14, s54, 8
	v_lshl_add_u32 v132, v130, 4, v131
	s_lshl_b32 s13, s13, 6
	v_ashrrev_i32_e32 v134, 2, v132
	v_and_b32_e32 v135, 3, v131
	v_lshlrev_b32_e32 v131, 4, v131
	s_add_i32 s13, s13, s14
	v_lshl_add_u32 v133, v130, 2, v131
	v_add_u32_e32 v130, s13, v134
	s_lshl_b32 s13, s56, 8
	s_lshl_b32 s12, s12, 5
	s_add_i32 s12, s12, s13
	v_and_b32_e32 v132, -4, v132
	v_lshl_or_b32 v134, v135, 3, s12
	v_ashrrev_i32_e32 v131, 31, v130
	v_lshl_add_u32 v132, v135, 6, v132
	v_ashrrev_i32_e32 v135, 31, v134
	v_lshlrev_b64 v[130:131], 10, v[130:131]
	v_lshl_add_u64 v[130:131], v[130:131], 0, v[134:135]
	v_readlane_b32 s14, v253, 11
	v_lshlrev_b64 v[130:131], 1, v[130:131]
	v_readlane_b32 s15, v253, 12
	v_lshl_add_u64 v[140:141], s[60:61], 0, v[130:131]
	s_mov_b64 s[12:13], 0x8000
	v_lshl_add_u64 v[138:139], s[14:15], 0, v[130:131]
	v_mov_b64_e32 v[130:131], v[138:139]
	global_load_dwordx4 v[146:149], v[130:131], off
	s_and_b64 vcc, exec, s[4:5]
	global_load_dwordx4 v[150:153], v[130:131], off offset:256
	s_mov_b64 s[12:13], 0x8000
	v_lshl_add_u64 v[130:131], v[138:139], 0, s[12:13]
	global_load_dwordx4 v[154:157], v[130:131], off
	global_load_dwordx4 v[158:161], v[130:131], off offset:256
	s_mov_b64 s[12:13], 0x10000
	v_lshl_add_u64 v[130:131], v[138:139], 0, s[12:13]
	global_load_dwordx4 v[162:165], v[130:131], off
	global_load_dwordx4 v[166:169], v[130:131], off offset:256
	s_mov_b64 s[12:13], 0x18000
	v_lshl_add_u64 v[130:131], v[138:139], 0, s[12:13]
	global_load_dwordx4 v[170:173], v[130:131], off
	global_load_dwordx4 v[174:177], v[130:131], off offset:256
	s_mov_b64 s[12:13], 0x40000
	v_lshl_add_u64 v[130:131], v[138:139], 0, s[12:13]
	global_load_dwordx4 v[178:181], v[130:131], off
	global_load_dwordx4 v[182:185], v[130:131], off offset:256
	s_mov_b64 s[12:13], 0x48000
	v_lshl_add_u64 v[130:131], v[138:139], 0, s[12:13]
	global_load_dwordx4 v[186:189], v[130:131], off
	global_load_dwordx4 v[190:193], v[130:131], off offset:256
	s_waitcnt vmcnt(11)
	ds_bpermute_b32 v143, v133, v147
	ds_bpermute_b32 v142, v133, v146
	ds_bpermute_b32 v145, v133, v149
	ds_bpermute_b32 v144, v133, v148
	v_mov_b64_e32 v[134:135], v[140:141]
	s_waitcnt lgkmcnt(3)
	v_lshlrev_b32_e32 v136, 16, v143
	v_and_b32_e32 v137, 0xffff0000, v143
	s_waitcnt lgkmcnt(2)
	v_and_b32_e32 v143, 0xffff0000, v142
	v_lshlrev_b32_e32 v142, 16, v142
	v_pk_mul_f32 v[136:137], v[136:137], s[96:97] op_sel_hi:[1,0]
	v_pk_fma_f32 v[128:129], v[128:129], 0.5, v[136:137] op_sel_hi:[1,0,1]
	v_pk_mul_f32 v[142:143], v[142:143], s[96:97] op_sel_hi:[1,0]
	v_pk_fma_f32 v[126:127], v[126:127], 0.5, v[142:143] op_sel_hi:[1,0,1]
	s_waitcnt lgkmcnt(1)
	v_lshlrev_b32_e32 v136, 16, v145
	v_and_b32_e32 v137, 0xffff0000, v145
	s_waitcnt lgkmcnt(0)
	v_and_b32_e32 v145, 0xffff0000, v144
	v_lshlrev_b32_e32 v144, 16, v144
	v_pk_mul_f32 v[136:137], v[136:137], s[96:97] op_sel_hi:[1,0]
	v_pk_fma_f32 v[124:125], v[124:125], 0.5, v[136:137] op_sel_hi:[1,0,1]
	v_pk_mul_f32 v[144:145], v[144:145], s[96:97] op_sel_hi:[1,0]
	v_pk_fma_f32 v[122:123], v[122:123], 0.5, v[144:145] op_sel_hi:[1,0,1]
	v_cvt_pk_bf16_f32 v126, v126, v127
	v_cvt_pk_bf16_f32 v127, v128, v129
	v_cvt_pk_bf16_f32 v128, v122, v123
	v_cvt_pk_bf16_f32 v125, v124, v125
	s_nop 1
	ds_bpermute_b32 v122, v132, v126
	ds_bpermute_b32 v123, v132, v127
	ds_bpermute_b32 v124, v132, v128
	ds_bpermute_b32 v125, v132, v125
	s_waitcnt lgkmcnt(0)
	global_store_dwordx4 v[134:135], v[122:125], off
	s_mov_b64 s[12:13], 0x50000
	v_lshl_add_u64 v[130:131], v[138:139], 0, s[12:13]
	global_load_dwordx4 v[126:129], v[130:131], off
	s_waitcnt vmcnt(12)
	ds_bpermute_b32 v143, v133, v151
	ds_bpermute_b32 v142, v133, v150
	ds_bpermute_b32 v145, v133, v153
	ds_bpermute_b32 v144, v133, v152
	s_waitcnt lgkmcnt(3)
	v_lshlrev_b32_e32 v136, 16, v143
	v_and_b32_e32 v137, 0xffff0000, v143
	s_waitcnt lgkmcnt(2)
	v_and_b32_e32 v143, 0xffff0000, v142
	v_lshlrev_b32_e32 v142, 16, v142
	v_pk_mul_f32 v[136:137], v[136:137], s[96:97] op_sel_hi:[1,0]
	v_pk_fma_f32 v[120:121], v[120:121], 0.5, v[136:137] op_sel_hi:[1,0,1]
	v_pk_mul_f32 v[142:143], v[142:143], s[96:97] op_sel_hi:[1,0]
	v_pk_fma_f32 v[118:119], v[118:119], 0.5, v[142:143] op_sel_hi:[1,0,1]
	s_waitcnt lgkmcnt(1)
	v_lshlrev_b32_e32 v136, 16, v145
	v_and_b32_e32 v137, 0xffff0000, v145
	s_waitcnt lgkmcnt(0)
	v_and_b32_e32 v145, 0xffff0000, v144
	v_lshlrev_b32_e32 v144, 16, v144
	v_pk_mul_f32 v[136:137], v[136:137], s[96:97] op_sel_hi:[1,0]
	v_pk_fma_f32 v[116:117], v[116:117], 0.5, v[136:137] op_sel_hi:[1,0,1]
	v_pk_mul_f32 v[144:145], v[144:145], s[96:97] op_sel_hi:[1,0]
	v_pk_fma_f32 v[114:115], v[114:115], 0.5, v[144:145] op_sel_hi:[1,0,1]
	v_cvt_pk_bf16_f32 v118, v118, v119
	v_cvt_pk_bf16_f32 v119, v120, v121
	v_cvt_pk_bf16_f32 v120, v114, v115
	v_cvt_pk_bf16_f32 v117, v116, v117
	s_nop 1
	ds_bpermute_b32 v114, v132, v118
	ds_bpermute_b32 v115, v132, v119
	ds_bpermute_b32 v116, v132, v120
	ds_bpermute_b32 v117, v132, v117
	s_waitcnt lgkmcnt(0)
	global_store_dwordx4 v[134:135], v[114:117], off offset:256
	global_load_dwordx4 v[118:121], v[130:131], off offset:256
	s_waitcnt vmcnt(13)
	ds_bpermute_b32 v143, v133, v155
	ds_bpermute_b32 v142, v133, v154
	ds_bpermute_b32 v145, v133, v157
	ds_bpermute_b32 v144, v133, v156
	s_mov_b64 s[12:13], 0x8000
	v_lshl_add_u64 v[134:135], v[140:141], 0, s[12:13]
	s_waitcnt lgkmcnt(3)
	v_lshlrev_b32_e32 v136, 16, v143
	v_and_b32_e32 v137, 0xffff0000, v143
	s_waitcnt lgkmcnt(2)
; #define GAS __attribute__((address_space(1)))
; __device__ __forceinline__ v4u tr4(int a, v4u x) { return (v4u){bperm(a, x.x), bperm(a, x.y), bperm(a, x.z), bperm(a, x.w)}; }
; __device__ __forceinline__ v4u pack8(const f32x4& a, const f32x4& b) { return (v4u){pg8::cvt_pk_bf16(a[0], a[1]), pg8::cvt_pk_bf16(a[2], a[3]), pg8::cvt_pk_bf16(b[0], b[1]), pg8::cvt_pk_bf16(b[2], b[3])}; }
;     __device__ __forceinline__ bool operator()(AccT& acc, const Unit& u, int wr, int wc, int fr, int fq) const {
;     ...
;         const int row0 = u.pm * 256 + wr * 64 + t.tfr, col0 = u.pn * 256 + wc * 32 + 8 * t.tfq;
; #pragma unroll
;         for (int ai = 0; ai < 2; ++ai)
; #pragma unroll
;             for (int m = 0; m < 4; ++m) { const size_t off = (size_t)(row0 + ai * 128 + m * 16) * D + col0;
; #pragma unroll
;                 for (int bj = 0; bj < 2; ++bj) { const v4u r = tr4(t.push, *(const GAS v4u*)(src + off + bj * 128));
;                     const f32x4 y0 = (f32x4){bflo(r.x), bfhi(r.x), bflo(r.y), bfhi(r.y)} * ca + acc[ai][bj][m][0] * cb, y1 = (f32x4){bflo(r.z), bfhi(r.z), bflo(r.w), bfhi(r.w)} * ca + acc[ai][bj][m][1] * cb;
;                     *(GAS v4u*)(dst + off + bj * 128) = tr4(t.pull, pack8(y0, y1)); } }
	v_and_b32_e32 v143, 0xffff0000, v142
	v_lshlrev_b32_e32 v142, 16, v142
	v_pk_mul_f32 v[136:137], v[136:137], s[96:97] op_sel_hi:[1,0]
	v_pk_fma_f32 v[112:113], v[112:113], 0.5, v[136:137] op_sel_hi:[1,0,1]
	v_pk_mul_f32 v[142:143], v[142:143], s[96:97] op_sel_hi:[1,0]
	v_pk_fma_f32 v[110:111], v[110:111], 0.5, v[142:143] op_sel_hi:[1,0,1]
	s_waitcnt lgkmcnt(1)
	v_lshlrev_b32_e32 v136, 16, v145
	v_and_b32_e32 v137, 0xffff0000, v145
	s_waitcnt lgkmcnt(0)
	v_and_b32_e32 v145, 0xffff0000, v144
	v_lshlrev_b32_e32 v144, 16, v144
	v_pk_mul_f32 v[136:137], v[136:137], s[96:97] op_sel_hi:[1,0]
	v_pk_fma_f32 v[108:109], v[108:109], 0.5, v[136:137] op_sel_hi:[1,0,1]
	v_pk_mul_f32 v[144:145], v[144:145], s[96:97] op_sel_hi:[1,0]
	v_pk_fma_f32 v[106:107], v[106:107], 0.5, v[144:145] op_sel_hi:[1,0,1]
	v_cvt_pk_bf16_f32 v110, v110, v111
	v_cvt_pk_bf16_f32 v111, v112, v113
	v_cvt_pk_bf16_f32 v112, v106, v107
	v_cvt_pk_bf16_f32 v109, v108, v109
	s_nop 1
	ds_bpermute_b32 v106, v132, v110
	ds_bpermute_b32 v107, v132, v111
	ds_bpermute_b32 v108, v132, v112
	ds_bpermute_b32 v109, v132, v109
	s_waitcnt lgkmcnt(0)
	global_store_dwordx4 v[134:135], v[106:109], off
	s_mov_b64 s[12:13], 0x58000
	v_lshl_add_u64 v[130:131], v[138:139], 0, s[12:13]
	global_load_dwordx4 v[110:113], v[130:131], off
	s_waitcnt vmcnt(14)
	ds_bpermute_b32 v143, v133, v159
	ds_bpermute_b32 v142, v133, v158
	ds_bpermute_b32 v145, v133, v161
	ds_bpermute_b32 v144, v133, v160
	s_waitcnt lgkmcnt(3)
	v_lshlrev_b32_e32 v136, 16, v143
	v_and_b32_e32 v137, 0xffff0000, v143
	s_waitcnt lgkmcnt(2)
	v_and_b32_e32 v143, 0xffff0000, v142
	v_lshlrev_b32_e32 v142, 16, v142
	v_pk_mul_f32 v[136:137], v[136:137], s[96:97] op_sel_hi:[1,0]
	v_pk_fma_f32 v[104:105], v[104:105], 0.5, v[136:137] op_sel_hi:[1,0,1]
	v_pk_mul_f32 v[142:143], v[142:143], s[96:97] op_sel_hi:[1,0]
	v_pk_fma_f32 v[102:103], v[102:103], 0.5, v[142:143] op_sel_hi:[1,0,1]
	s_waitcnt lgkmcnt(1)
	v_lshlrev_b32_e32 v136, 16, v145
	v_and_b32_e32 v137, 0xffff0000, v145
	s_waitcnt lgkmcnt(0)
	v_and_b32_e32 v145, 0xffff0000, v144
	v_lshlrev_b32_e32 v144, 16, v144
	v_pk_mul_f32 v[136:137], v[136:137], s[96:97] op_sel_hi:[1,0]
	v_pk_fma_f32 v[100:101], v[100:101], 0.5, v[136:137] op_sel_hi:[1,0,1]
	v_pk_mul_f32 v[144:145], v[144:145], s[96:97] op_sel_hi:[1,0]
	v_pk_fma_f32 v[98:99], v[98:99], 0.5, v[144:145] op_sel_hi:[1,0,1]
	v_cvt_pk_bf16_f32 v102, v102, v103
	v_cvt_pk_bf16_f32 v103, v104, v105
	v_cvt_pk_bf16_f32 v104, v98, v99
	v_cvt_pk_bf16_f32 v101, v100, v101
	s_nop 1
	ds_bpermute_b32 v98, v132, v102
	ds_bpermute_b32 v99, v132, v103
	ds_bpermute_b32 v100, v132, v104
	ds_bpermute_b32 v101, v132, v101
	s_waitcnt lgkmcnt(0)
	global_store_dwordx4 v[134:135], v[98:101], off offset:256
	global_load_dwordx4 v[102:105], v[130:131], off offset:256
	s_waitcnt vmcnt(15)
	ds_bpermute_b32 v143, v133, v163
	ds_bpermute_b32 v142, v133, v162
	ds_bpermute_b32 v145, v133, v165
	ds_bpermute_b32 v144, v133, v164
	s_mov_b64 s[12:13], 0x10000
	v_lshl_add_u64 v[134:135], v[140:141], 0, s[12:13]
	s_waitcnt lgkmcnt(3)
	v_lshlrev_b32_e32 v136, 16, v143
	v_and_b32_e32 v137, 0xffff0000, v143
	s_waitcnt lgkmcnt(2)
	v_and_b32_e32 v143, 0xffff0000, v142
	v_lshlrev_b32_e32 v142, 16, v142
	v_pk_mul_f32 v[136:137], v[136:137], s[96:97] op_sel_hi:[1,0]
	v_pk_fma_f32 v[96:97], v[96:97], 0.5, v[136:137] op_sel_hi:[1,0,1]
	v_pk_mul_f32 v[142:143], v[142:143], s[96:97] op_sel_hi:[1,0]
	v_pk_fma_f32 v[94:95], v[94:95], 0.5, v[142:143] op_sel_hi:[1,0,1]
	s_waitcnt lgkmcnt(1)
	v_lshlrev_b32_e32 v136, 16, v145
	v_and_b32_e32 v137, 0xffff0000, v145
	s_waitcnt lgkmcnt(0)
	v_and_b32_e32 v145, 0xffff0000, v144
	v_lshlrev_b32_e32 v144, 16, v144
	v_pk_mul_f32 v[136:137], v[136:137], s[96:97] op_sel_hi:[1,0]
	v_pk_fma_f32 v[92:93], v[92:93], 0.5, v[136:137] op_sel_hi:[1,0,1]
	v_pk_mul_f32 v[144:145], v[144:145], s[96:97] op_sel_hi:[1,0]
	v_pk_fma_f32 v[90:91], v[90:91], 0.5, v[144:145] op_sel_hi:[1,0,1]
	v_cvt_pk_bf16_f32 v94, v94, v95
	v_cvt_pk_bf16_f32 v95, v96, v97
	v_cvt_pk_bf16_f32 v96, v90, v91
	v_cvt_pk_bf16_f32 v93, v92, v93
	s_nop 1
	ds_bpermute_b32 v90, v132, v94
	ds_bpermute_b32 v91, v132, v95
	ds_bpermute_b32 v92, v132, v96
	ds_bpermute_b32 v93, v132, v93
	s_waitcnt lgkmcnt(0)
	global_store_dwordx4 v[134:135], v[90:93], off
	s_waitcnt vmcnt(15)
	ds_bpermute_b32 v143, v133, v167
	ds_bpermute_b32 v142, v133, v166
	ds_bpermute_b32 v145, v133, v169
	ds_bpermute_b32 v144, v133, v168
	s_waitcnt lgkmcnt(3)
	v_lshlrev_b32_e32 v136, 16, v143
	v_and_b32_e32 v137, 0xffff0000, v143
	s_waitcnt lgkmcnt(2)
	v_and_b32_e32 v143, 0xffff0000, v142
	v_lshlrev_b32_e32 v142, 16, v142
	v_pk_mul_f32 v[136:137], v[136:137], s[96:97] op_sel_hi:[1,0]
	v_pk_fma_f32 v[88:89], v[88:89], 0.5, v[136:137] op_sel_hi:[1,0,1]
	v_pk_mul_f32 v[142:143], v[142:143], s[96:97] op_sel_hi:[1,0]
	v_pk_fma_f32 v[86:87], v[86:87], 0.5, v[142:143] op_sel_hi:[1,0,1]
	s_waitcnt lgkmcnt(1)
	v_lshlrev_b32_e32 v136, 16, v145
	v_and_b32_e32 v137, 0xffff0000, v145
	s_waitcnt lgkmcnt(0)
	v_and_b32_e32 v145, 0xffff0000, v144
	v_lshlrev_b32_e32 v144, 16, v144
	v_pk_mul_f32 v[136:137], v[136:137], s[96:97] op_sel_hi:[1,0]
	v_pk_fma_f32 v[84:85], v[84:85], 0.5, v[136:137] op_sel_hi:[1,0,1]
	v_pk_mul_f32 v[144:145], v[144:145], s[96:97] op_sel_hi:[1,0]
	v_pk_fma_f32 v[82:83], v[82:83], 0.5, v[144:145] op_sel_hi:[1,0,1]
	v_cvt_pk_bf16_f32 v86, v86, v87
	v_cvt_pk_bf16_f32 v87, v88, v89
	v_cvt_pk_bf16_f32 v88, v82, v83
	v_cvt_pk_bf16_f32 v85, v84, v85
	s_nop 1
	ds_bpermute_b32 v82, v132, v86
	ds_bpermute_b32 v83, v132, v87
	ds_bpermute_b32 v84, v132, v88
	ds_bpermute_b32 v85, v132, v85
	s_waitcnt lgkmcnt(0)
; #define GAS __attribute__((address_space(1)))
; __device__ __forceinline__ v4u tr4(int a, v4u x) { return (v4u){bperm(a, x.x), bperm(a, x.y), bperm(a, x.z), bperm(a, x.w)}; }
; __device__ __forceinline__ v4u pack8(const f32x4& a, const f32x4& b) { return (v4u){pg8::cvt_pk_bf16(a[0], a[1]), pg8::cvt_pk_bf16(a[2], a[3]), pg8::cvt_pk_bf16(b[0], b[1]), pg8::cvt_pk_bf16(b[2], b[3])}; }
;     __device__ __forceinline__ bool operator()(AccT& acc, const Unit& u, int wr, int wc, int fr, int fq) const {
;     ...
;         const int row0 = u.pm * 256 + wr * 64 + t.tfr, col0 = u.pn * 256 + wc * 32 + 8 * t.tfq;
; #pragma unroll
;         for (int ai = 0; ai < 2; ++ai)
; #pragma unroll
;             for (int m = 0; m < 4; ++m) { const size_t off = (size_t)(row0 + ai * 128 + m * 16) * D + col0;
; #pragma unroll
;                 for (int bj = 0; bj < 2; ++bj) { const v4u r = tr4(t.push, *(const GAS v4u*)(src + off + bj * 128));
;                     const f32x4 y0 = (f32x4){bflo(r.x), bfhi(r.x), bflo(r.y), bfhi(r.y)} * ca + acc[ai][bj][m][0] * cb, y1 = (f32x4){bflo(r.z), bfhi(r.z), bflo(r.w), bfhi(r.w)} * ca + acc[ai][bj][m][1] * cb;
;                     *(GAS v4u*)(dst + off + bj * 128) = tr4(t.pull, pack8(y0, y1)); } }
	global_store_dwordx4 v[134:135], v[82:85], off offset:256
	s_waitcnt vmcnt(15)
	ds_bpermute_b32 v143, v133, v171
	ds_bpermute_b32 v142, v133, v170
	ds_bpermute_b32 v145, v133, v173
	ds_bpermute_b32 v144, v133, v172
	s_mov_b64 s[12:13], 0x18000
	v_lshl_add_u64 v[134:135], v[140:141], 0, s[12:13]
	s_waitcnt lgkmcnt(3)
	v_lshlrev_b32_e32 v136, 16, v143
	v_and_b32_e32 v137, 0xffff0000, v143
	s_waitcnt lgkmcnt(2)
	v_and_b32_e32 v143, 0xffff0000, v142
	v_lshlrev_b32_e32 v142, 16, v142
	v_pk_mul_f32 v[136:137], v[136:137], s[96:97] op_sel_hi:[1,0]
	v_pk_fma_f32 v[80:81], v[80:81], 0.5, v[136:137] op_sel_hi:[1,0,1]
	v_pk_mul_f32 v[142:143], v[142:143], s[96:97] op_sel_hi:[1,0]
	v_pk_fma_f32 v[78:79], v[78:79], 0.5, v[142:143] op_sel_hi:[1,0,1]
	s_waitcnt lgkmcnt(1)
	v_lshlrev_b32_e32 v136, 16, v145
	v_and_b32_e32 v137, 0xffff0000, v145
	s_waitcnt lgkmcnt(0)
	v_and_b32_e32 v145, 0xffff0000, v144
	v_lshlrev_b32_e32 v144, 16, v144
	v_pk_mul_f32 v[136:137], v[136:137], s[96:97] op_sel_hi:[1,0]
	v_pk_fma_f32 v[76:77], v[76:77], 0.5, v[136:137] op_sel_hi:[1,0,1]
	v_pk_mul_f32 v[144:145], v[144:145], s[96:97] op_sel_hi:[1,0]
	v_pk_fma_f32 v[74:75], v[74:75], 0.5, v[144:145] op_sel_hi:[1,0,1]
	v_cvt_pk_bf16_f32 v78, v78, v79
	v_cvt_pk_bf16_f32 v79, v80, v81
	v_cvt_pk_bf16_f32 v80, v74, v75
	v_cvt_pk_bf16_f32 v77, v76, v77
	s_nop 1
	ds_bpermute_b32 v74, v132, v78
	ds_bpermute_b32 v75, v132, v79
	ds_bpermute_b32 v76, v132, v80
	ds_bpermute_b32 v77, v132, v77
	s_waitcnt lgkmcnt(0)
	global_store_dwordx4 v[134:135], v[74:77], off
	s_waitcnt vmcnt(15)
	ds_bpermute_b32 v143, v133, v175
	ds_bpermute_b32 v142, v133, v174
	ds_bpermute_b32 v145, v133, v177
	ds_bpermute_b32 v144, v133, v176
	s_waitcnt lgkmcnt(3)
	v_lshlrev_b32_e32 v136, 16, v143
	v_and_b32_e32 v137, 0xffff0000, v143
	s_waitcnt lgkmcnt(2)
	v_and_b32_e32 v143, 0xffff0000, v142
	v_lshlrev_b32_e32 v142, 16, v142
	v_pk_mul_f32 v[136:137], v[136:137], s[96:97] op_sel_hi:[1,0]
	v_pk_fma_f32 v[72:73], v[72:73], 0.5, v[136:137] op_sel_hi:[1,0,1]
	v_pk_mul_f32 v[142:143], v[142:143], s[96:97] op_sel_hi:[1,0]
	v_pk_fma_f32 v[70:71], v[70:71], 0.5, v[142:143] op_sel_hi:[1,0,1]
	s_waitcnt lgkmcnt(1)
	v_lshlrev_b32_e32 v136, 16, v145
	v_and_b32_e32 v137, 0xffff0000, v145
	s_waitcnt lgkmcnt(0)
	v_and_b32_e32 v145, 0xffff0000, v144
	v_lshlrev_b32_e32 v144, 16, v144
	v_pk_mul_f32 v[136:137], v[136:137], s[96:97] op_sel_hi:[1,0]
	v_pk_fma_f32 v[68:69], v[68:69], 0.5, v[136:137] op_sel_hi:[1,0,1]
	v_pk_mul_f32 v[144:145], v[144:145], s[96:97] op_sel_hi:[1,0]
	v_pk_fma_f32 v[66:67], v[66:67], 0.5, v[144:145] op_sel_hi:[1,0,1]
	v_cvt_pk_bf16_f32 v70, v70, v71
	v_cvt_pk_bf16_f32 v71, v72, v73
	v_cvt_pk_bf16_f32 v72, v66, v67
	v_cvt_pk_bf16_f32 v69, v68, v69
	s_nop 1
	ds_bpermute_b32 v66, v132, v70
	ds_bpermute_b32 v67, v132, v71
	ds_bpermute_b32 v68, v132, v72
	ds_bpermute_b32 v69, v132, v69
	s_waitcnt lgkmcnt(0)
	global_store_dwordx4 v[134:135], v[66:69], off offset:256
	s_waitcnt vmcnt(15)
	ds_bpermute_b32 v143, v133, v179
	ds_bpermute_b32 v142, v133, v178
	ds_bpermute_b32 v145, v133, v181
	ds_bpermute_b32 v144, v133, v180
	s_mov_b64 s[12:13], 0x40000
	v_lshl_add_u64 v[134:135], v[140:141], 0, s[12:13]
	s_waitcnt lgkmcnt(3)
	v_lshlrev_b32_e32 v136, 16, v143
	v_and_b32_e32 v137, 0xffff0000, v143
	s_waitcnt lgkmcnt(2)
	v_and_b32_e32 v143, 0xffff0000, v142
	v_lshlrev_b32_e32 v142, 16, v142
	v_pk_mul_f32 v[136:137], v[136:137], s[96:97] op_sel_hi:[1,0]
	v_pk_fma_f32 v[64:65], v[64:65], 0.5, v[136:137] op_sel_hi:[1,0,1]
	v_pk_mul_f32 v[142:143], v[142:143], s[96:97] op_sel_hi:[1,0]
	v_pk_fma_f32 v[62:63], v[62:63], 0.5, v[142:143] op_sel_hi:[1,0,1]
	s_waitcnt lgkmcnt(1)
	v_lshlrev_b32_e32 v136, 16, v145
	v_and_b32_e32 v137, 0xffff0000, v145
	s_waitcnt lgkmcnt(0)
	v_and_b32_e32 v145, 0xffff0000, v144
	v_lshlrev_b32_e32 v144, 16, v144
	v_pk_mul_f32 v[136:137], v[136:137], s[96:97] op_sel_hi:[1,0]
	v_pk_fma_f32 v[60:61], v[60:61], 0.5, v[136:137] op_sel_hi:[1,0,1]
	v_pk_mul_f32 v[144:145], v[144:145], s[96:97] op_sel_hi:[1,0]
	v_pk_fma_f32 v[58:59], v[58:59], 0.5, v[144:145] op_sel_hi:[1,0,1]
	v_cvt_pk_bf16_f32 v62, v62, v63
	v_cvt_pk_bf16_f32 v63, v64, v65
	v_cvt_pk_bf16_f32 v64, v58, v59
	v_cvt_pk_bf16_f32 v61, v60, v61
	s_nop 1
	ds_bpermute_b32 v58, v132, v62
	ds_bpermute_b32 v59, v132, v63
	ds_bpermute_b32 v60, v132, v64
	ds_bpermute_b32 v61, v132, v61
	s_waitcnt lgkmcnt(0)
	global_store_dwordx4 v[134:135], v[58:61], off
	s_waitcnt vmcnt(15)
	ds_bpermute_b32 v143, v133, v183
	ds_bpermute_b32 v142, v133, v182
	ds_bpermute_b32 v145, v133, v185
	ds_bpermute_b32 v144, v133, v184
	s_waitcnt lgkmcnt(3)
	v_lshlrev_b32_e32 v136, 16, v143
	v_and_b32_e32 v137, 0xffff0000, v143
	s_waitcnt lgkmcnt(2)
	v_and_b32_e32 v143, 0xffff0000, v142
	v_lshlrev_b32_e32 v142, 16, v142
	v_pk_mul_f32 v[136:137], v[136:137], s[96:97] op_sel_hi:[1,0]
	v_pk_fma_f32 v[56:57], v[56:57], 0.5, v[136:137] op_sel_hi:[1,0,1]
	v_pk_mul_f32 v[142:143], v[142:143], s[96:97] op_sel_hi:[1,0]
	v_pk_fma_f32 v[54:55], v[54:55], 0.5, v[142:143] op_sel_hi:[1,0,1]
	s_waitcnt lgkmcnt(1)
	v_lshlrev_b32_e32 v136, 16, v145
	v_and_b32_e32 v137, 0xffff0000, v145
	s_waitcnt lgkmcnt(0)
	v_and_b32_e32 v145, 0xffff0000, v144
	v_lshlrev_b32_e32 v144, 16, v144
	v_pk_mul_f32 v[136:137], v[136:137], s[96:97] op_sel_hi:[1,0]
	v_pk_fma_f32 v[52:53], v[52:53], 0.5, v[136:137] op_sel_hi:[1,0,1]
	v_pk_mul_f32 v[144:145], v[144:145], s[96:97] op_sel_hi:[1,0]
	v_pk_fma_f32 v[50:51], v[50:51], 0.5, v[144:145] op_sel_hi:[1,0,1]
	v_cvt_pk_bf16_f32 v54, v54, v55
	v_cvt_pk_bf16_f32 v55, v56, v57
	v_cvt_pk_bf16_f32 v56, v50, v51
	v_cvt_pk_bf16_f32 v53, v52, v53
	s_nop 1
	ds_bpermute_b32 v50, v132, v54
	ds_bpermute_b32 v51, v132, v55
	ds_bpermute_b32 v52, v132, v56
	ds_bpermute_b32 v53, v132, v53
	s_waitcnt lgkmcnt(0)
; #define GAS __attribute__((address_space(1)))
; __device__ __forceinline__ v4u tr4(int a, v4u x) { return (v4u){bperm(a, x.x), bperm(a, x.y), bperm(a, x.z), bperm(a, x.w)}; }
; __device__ __forceinline__ v4u pack8(const f32x4& a, const f32x4& b) { return (v4u){pg8::cvt_pk_bf16(a[0], a[1]), pg8::cvt_pk_bf16(a[2], a[3]), pg8::cvt_pk_bf16(b[0], b[1]), pg8::cvt_pk_bf16(b[2], b[3])}; }
;     __device__ __forceinline__ bool operator()(AccT& acc, const Unit& u, int wr, int wc, int fr, int fq) const {
;     ...
;         const int row0 = u.pm * 256 + wr * 64 + t.tfr, col0 = u.pn * 256 + wc * 32 + 8 * t.tfq;
; #pragma unroll
;         for (int ai = 0; ai < 2; ++ai)
; #pragma unroll
;             for (int m = 0; m < 4; ++m) { const size_t off = (size_t)(row0 + ai * 128 + m * 16) * D + col0;
; #pragma unroll
;                 for (int bj = 0; bj < 2; ++bj) { const v4u r = tr4(t.push, *(const GAS v4u*)(src + off + bj * 128));
;                     const f32x4 y0 = (f32x4){bflo(r.x), bfhi(r.x), bflo(r.y), bfhi(r.y)} * ca + acc[ai][bj][m][0] * cb, y1 = (f32x4){bflo(r.z), bfhi(r.z), bflo(r.w), bfhi(r.w)} * ca + acc[ai][bj][m][1] * cb;
;                     *(GAS v4u*)(dst + off + bj * 128) = tr4(t.pull, pack8(y0, y1)); } }
	global_store_dwordx4 v[134:135], v[50:53], off offset:256
	s_waitcnt vmcnt(15)
	ds_bpermute_b32 v143, v133, v187
	ds_bpermute_b32 v142, v133, v186
	ds_bpermute_b32 v145, v133, v189
	ds_bpermute_b32 v144, v133, v188
	s_mov_b64 s[12:13], 0x48000
	v_lshl_add_u64 v[134:135], v[140:141], 0, s[12:13]
	s_waitcnt lgkmcnt(3)
	v_lshlrev_b32_e32 v136, 16, v143
	v_and_b32_e32 v137, 0xffff0000, v143
	s_waitcnt lgkmcnt(2)
	v_and_b32_e32 v143, 0xffff0000, v142
	v_lshlrev_b32_e32 v142, 16, v142
	v_pk_mul_f32 v[136:137], v[136:137], s[96:97] op_sel_hi:[1,0]
	v_pk_fma_f32 v[48:49], v[48:49], 0.5, v[136:137] op_sel_hi:[1,0,1]
	v_pk_mul_f32 v[142:143], v[142:143], s[96:97] op_sel_hi:[1,0]
	v_pk_fma_f32 v[46:47], v[46:47], 0.5, v[142:143] op_sel_hi:[1,0,1]
	s_waitcnt lgkmcnt(1)
	v_lshlrev_b32_e32 v136, 16, v145
	v_and_b32_e32 v137, 0xffff0000, v145
	s_waitcnt lgkmcnt(0)
	v_and_b32_e32 v145, 0xffff0000, v144
	v_lshlrev_b32_e32 v144, 16, v144
	v_pk_mul_f32 v[136:137], v[136:137], s[96:97] op_sel_hi:[1,0]
	v_pk_fma_f32 v[44:45], v[44:45], 0.5, v[136:137] op_sel_hi:[1,0,1]
	v_pk_mul_f32 v[144:145], v[144:145], s[96:97] op_sel_hi:[1,0]
	v_pk_fma_f32 v[42:43], v[42:43], 0.5, v[144:145] op_sel_hi:[1,0,1]
	v_cvt_pk_bf16_f32 v46, v46, v47
	v_cvt_pk_bf16_f32 v47, v48, v49
	v_cvt_pk_bf16_f32 v48, v42, v43
	v_cvt_pk_bf16_f32 v45, v44, v45
	s_nop 1
	ds_bpermute_b32 v42, v132, v46
	ds_bpermute_b32 v43, v132, v47
	ds_bpermute_b32 v44, v132, v48
	ds_bpermute_b32 v45, v132, v45
	s_waitcnt lgkmcnt(0)
	global_store_dwordx4 v[134:135], v[42:45], off
	s_waitcnt vmcnt(15)
	ds_bpermute_b32 v143, v133, v191
	ds_bpermute_b32 v142, v133, v190
	ds_bpermute_b32 v145, v133, v193
	ds_bpermute_b32 v144, v133, v192
	s_waitcnt lgkmcnt(3)
	v_lshlrev_b32_e32 v136, 16, v143
	v_and_b32_e32 v137, 0xffff0000, v143
	s_waitcnt lgkmcnt(2)
	v_and_b32_e32 v143, 0xffff0000, v142
	v_lshlrev_b32_e32 v142, 16, v142
	v_pk_mul_f32 v[136:137], v[136:137], s[96:97] op_sel_hi:[1,0]
	v_pk_fma_f32 v[40:41], v[40:41], 0.5, v[136:137] op_sel_hi:[1,0,1]
	v_pk_mul_f32 v[142:143], v[142:143], s[96:97] op_sel_hi:[1,0]
	v_pk_fma_f32 v[38:39], v[38:39], 0.5, v[142:143] op_sel_hi:[1,0,1]
	s_waitcnt lgkmcnt(1)
	v_lshlrev_b32_e32 v136, 16, v145
	v_and_b32_e32 v137, 0xffff0000, v145
	s_waitcnt lgkmcnt(0)
	v_and_b32_e32 v145, 0xffff0000, v144
	v_lshlrev_b32_e32 v144, 16, v144
	v_pk_mul_f32 v[136:137], v[136:137], s[96:97] op_sel_hi:[1,0]
	v_pk_fma_f32 v[36:37], v[36:37], 0.5, v[136:137] op_sel_hi:[1,0,1]
	v_pk_mul_f32 v[144:145], v[144:145], s[96:97] op_sel_hi:[1,0]
	v_pk_fma_f32 v[34:35], v[34:35], 0.5, v[144:145] op_sel_hi:[1,0,1]
	v_cvt_pk_bf16_f32 v38, v38, v39
	v_cvt_pk_bf16_f32 v39, v40, v41
	v_cvt_pk_bf16_f32 v40, v34, v35
	v_cvt_pk_bf16_f32 v37, v36, v37
	s_nop 1
	ds_bpermute_b32 v34, v132, v38
	ds_bpermute_b32 v35, v132, v39
	ds_bpermute_b32 v36, v132, v40
	ds_bpermute_b32 v37, v132, v37
	s_waitcnt lgkmcnt(0)
	global_store_dwordx4 v[134:135], v[34:37], off offset:256
	s_waitcnt vmcnt(14)
	ds_bpermute_b32 v143, v133, v127
	ds_bpermute_b32 v142, v133, v126
	ds_bpermute_b32 v145, v133, v129
	ds_bpermute_b32 v144, v133, v128
	s_mov_b64 s[12:13], 0x50000
	v_lshl_add_u64 v[134:135], v[140:141], 0, s[12:13]
	s_waitcnt lgkmcnt(3)
	v_lshlrev_b32_e32 v136, 16, v143
	v_and_b32_e32 v137, 0xffff0000, v143
	s_waitcnt lgkmcnt(2)
	v_and_b32_e32 v143, 0xffff0000, v142
	v_lshlrev_b32_e32 v142, 16, v142
	v_pk_mul_f32 v[136:137], v[136:137], s[96:97] op_sel_hi:[1,0]
	v_pk_fma_f32 v[32:33], v[32:33], 0.5, v[136:137] op_sel_hi:[1,0,1]
	v_pk_mul_f32 v[142:143], v[142:143], s[96:97] op_sel_hi:[1,0]
	v_pk_fma_f32 v[30:31], v[30:31], 0.5, v[142:143] op_sel_hi:[1,0,1]
	s_waitcnt lgkmcnt(1)
	v_lshlrev_b32_e32 v136, 16, v145
	v_and_b32_e32 v137, 0xffff0000, v145
	s_waitcnt lgkmcnt(0)
	v_and_b32_e32 v145, 0xffff0000, v144
	v_lshlrev_b32_e32 v144, 16, v144
	v_pk_mul_f32 v[136:137], v[136:137], s[96:97] op_sel_hi:[1,0]
	v_pk_fma_f32 v[28:29], v[28:29], 0.5, v[136:137] op_sel_hi:[1,0,1]
	v_pk_mul_f32 v[144:145], v[144:145], s[96:97] op_sel_hi:[1,0]
	v_pk_fma_f32 v[26:27], v[26:27], 0.5, v[144:145] op_sel_hi:[1,0,1]
	v_cvt_pk_bf16_f32 v30, v30, v31
	v_cvt_pk_bf16_f32 v31, v32, v33
	v_cvt_pk_bf16_f32 v32, v26, v27
	v_cvt_pk_bf16_f32 v29, v28, v29
	s_nop 1
	ds_bpermute_b32 v26, v132, v30
	ds_bpermute_b32 v27, v132, v31
	ds_bpermute_b32 v28, v132, v32
	ds_bpermute_b32 v29, v132, v29
	s_waitcnt lgkmcnt(0)
; #define PG8_BAR __builtin_amdgcn_s_barrier()
; #define GAS __attribute__((address_space(1)))
; __device__ __forceinline__ v4u tr4(int a, v4u x) { return (v4u){bperm(a, x.x), bperm(a, x.y), bperm(a, x.z), bperm(a, x.w)}; }
; __device__ __forceinline__ v4u pack8(const f32x4& a, const f32x4& b) { return (v4u){pg8::cvt_pk_bf16(a[0], a[1]), pg8::cvt_pk_bf16(a[2], a[3]), pg8::cvt_pk_bf16(b[0], b[1]), pg8::cvt_pk_bf16(b[2], b[3])}; }
; template <class Epi, class Sched, bool ALIGN_EPI = false, bool SP2 = false>
; __device__ __forceinline__ void gemm_phase(PG8_LAS unsigned char* lds, const Gemm g, const Sched& S, const Epi& E, const int wave_id) {
;     ...
;         cur = nxt; cA = nA; cB = nB; ++ui;
;         if constexpr (ALIGN_EPI) { if (wr == 1) PG8_BAR; }
;     __device__ __forceinline__ bool operator()(AccT& acc, const Unit& u, int wr, int wc, int fr, int fq) const {
;     ...
;         const int row0 = u.pm * 256 + wr * 64 + t.tfr, col0 = u.pn * 256 + wc * 32 + 8 * t.tfq;
; #pragma unroll
;         for (int ai = 0; ai < 2; ++ai)
; #pragma unroll
;             for (int m = 0; m < 4; ++m) { const size_t off = (size_t)(row0 + ai * 128 + m * 16) * D + col0;
; #pragma unroll
;                 for (int bj = 0; bj < 2; ++bj) { const v4u r = tr4(t.push, *(const GAS v4u*)(src + off + bj * 128));
;                     const f32x4 y0 = (f32x4){bflo(r.x), bfhi(r.x), bflo(r.y), bfhi(r.y)} * ca + acc[ai][bj][m][0] * cb, y1 = (f32x4){bflo(r.z), bfhi(r.z), bflo(r.w), bfhi(r.w)} * ca + acc[ai][bj][m][1] * cb;
;                     *(GAS v4u*)(dst + off + bj * 128) = tr4(t.pull, pack8(y0, y1)); } }
	global_store_dwordx4 v[134:135], v[26:29], off
	s_waitcnt vmcnt(13)
	ds_bpermute_b32 v143, v133, v119
	ds_bpermute_b32 v142, v133, v118
	ds_bpermute_b32 v145, v133, v121
	ds_bpermute_b32 v144, v133, v120
	s_waitcnt lgkmcnt(3)
	v_lshlrev_b32_e32 v136, 16, v143
	v_and_b32_e32 v137, 0xffff0000, v143
	s_waitcnt lgkmcnt(2)
	v_and_b32_e32 v143, 0xffff0000, v142
	v_lshlrev_b32_e32 v142, 16, v142
	v_pk_mul_f32 v[136:137], v[136:137], s[96:97] op_sel_hi:[1,0]
	v_pk_fma_f32 v[24:25], v[24:25], 0.5, v[136:137] op_sel_hi:[1,0,1]
	v_pk_mul_f32 v[142:143], v[142:143], s[96:97] op_sel_hi:[1,0]
	v_pk_fma_f32 v[22:23], v[22:23], 0.5, v[142:143] op_sel_hi:[1,0,1]
	s_waitcnt lgkmcnt(1)
	v_lshlrev_b32_e32 v136, 16, v145
	v_and_b32_e32 v137, 0xffff0000, v145
	s_waitcnt lgkmcnt(0)
	v_and_b32_e32 v145, 0xffff0000, v144
	v_lshlrev_b32_e32 v144, 16, v144
	v_pk_mul_f32 v[136:137], v[136:137], s[96:97] op_sel_hi:[1,0]
	v_pk_fma_f32 v[20:21], v[20:21], 0.5, v[136:137] op_sel_hi:[1,0,1]
	v_pk_mul_f32 v[144:145], v[144:145], s[96:97] op_sel_hi:[1,0]
	v_pk_fma_f32 v[18:19], v[18:19], 0.5, v[144:145] op_sel_hi:[1,0,1]
	v_cvt_pk_bf16_f32 v22, v22, v23
	v_cvt_pk_bf16_f32 v23, v24, v25
	v_cvt_pk_bf16_f32 v24, v18, v19
	v_cvt_pk_bf16_f32 v21, v20, v21
	s_nop 1
	ds_bpermute_b32 v18, v132, v22
	ds_bpermute_b32 v19, v132, v23
	ds_bpermute_b32 v20, v132, v24
	ds_bpermute_b32 v21, v132, v21
	s_waitcnt lgkmcnt(0)
	global_store_dwordx4 v[134:135], v[18:21], off offset:256
	s_waitcnt vmcnt(12)
	ds_bpermute_b32 v143, v133, v111
	ds_bpermute_b32 v142, v133, v110
	ds_bpermute_b32 v145, v133, v113
	ds_bpermute_b32 v144, v133, v112
	s_mov_b64 s[12:13], 0x58000
	v_lshl_add_u64 v[134:135], v[140:141], 0, s[12:13]
	s_waitcnt lgkmcnt(3)
	v_lshlrev_b32_e32 v136, 16, v143
	v_and_b32_e32 v137, 0xffff0000, v143
	s_waitcnt lgkmcnt(2)
	v_and_b32_e32 v143, 0xffff0000, v142
	v_lshlrev_b32_e32 v142, 16, v142
	v_pk_mul_f32 v[136:137], v[136:137], s[96:97] op_sel_hi:[1,0]
	v_pk_fma_f32 v[16:17], v[16:17], 0.5, v[136:137] op_sel_hi:[1,0,1]
	v_pk_mul_f32 v[142:143], v[142:143], s[96:97] op_sel_hi:[1,0]
	v_pk_fma_f32 v[14:15], v[14:15], 0.5, v[142:143] op_sel_hi:[1,0,1]
	s_waitcnt lgkmcnt(1)
	v_lshlrev_b32_e32 v136, 16, v145
	v_and_b32_e32 v137, 0xffff0000, v145
	s_waitcnt lgkmcnt(0)
	v_and_b32_e32 v145, 0xffff0000, v144
	v_lshlrev_b32_e32 v144, 16, v144
	v_pk_mul_f32 v[136:137], v[136:137], s[96:97] op_sel_hi:[1,0]
	v_pk_fma_f32 v[12:13], v[12:13], 0.5, v[136:137] op_sel_hi:[1,0,1]
	v_pk_mul_f32 v[144:145], v[144:145], s[96:97] op_sel_hi:[1,0]
	v_pk_fma_f32 v[10:11], v[10:11], 0.5, v[144:145] op_sel_hi:[1,0,1]
	v_cvt_pk_bf16_f32 v14, v14, v15
	v_cvt_pk_bf16_f32 v15, v16, v17
	v_cvt_pk_bf16_f32 v16, v10, v11
	v_cvt_pk_bf16_f32 v13, v12, v13
	s_nop 1
	ds_bpermute_b32 v10, v132, v14
	ds_bpermute_b32 v11, v132, v15
	ds_bpermute_b32 v12, v132, v16
	ds_bpermute_b32 v13, v132, v13
	s_waitcnt lgkmcnt(0)
	global_store_dwordx4 v[134:135], v[10:13], off
	s_waitcnt vmcnt(11)
	ds_bpermute_b32 v143, v133, v103
	ds_bpermute_b32 v142, v133, v102
	ds_bpermute_b32 v145, v133, v105
	ds_bpermute_b32 v144, v133, v104
	s_waitcnt lgkmcnt(3)
	v_lshlrev_b32_e32 v136, 16, v143
	v_and_b32_e32 v137, 0xffff0000, v143
	s_waitcnt lgkmcnt(2)
	v_and_b32_e32 v143, 0xffff0000, v142
	v_lshlrev_b32_e32 v142, 16, v142
	v_pk_mul_f32 v[136:137], v[136:137], s[96:97] op_sel_hi:[1,0]
	v_pk_fma_f32 v[8:9], v[8:9], 0.5, v[136:137] op_sel_hi:[1,0,1]
	v_pk_mul_f32 v[142:143], v[142:143], s[96:97] op_sel_hi:[1,0]
	v_pk_fma_f32 v[6:7], v[6:7], 0.5, v[142:143] op_sel_hi:[1,0,1]
	s_waitcnt lgkmcnt(1)
	v_lshlrev_b32_e32 v136, 16, v145
	v_and_b32_e32 v137, 0xffff0000, v145
	s_waitcnt lgkmcnt(0)
	v_and_b32_e32 v145, 0xffff0000, v144
	v_lshlrev_b32_e32 v144, 16, v144
	v_pk_mul_f32 v[136:137], v[136:137], s[96:97] op_sel_hi:[1,0]
	v_pk_fma_f32 v[4:5], v[4:5], 0.5, v[136:137] op_sel_hi:[1,0,1]
	v_pk_mul_f32 v[144:145], v[144:145], s[96:97] op_sel_hi:[1,0]
	v_pk_fma_f32 v[2:3], v[2:3], 0.5, v[144:145] op_sel_hi:[1,0,1]
	v_cvt_pk_bf16_f32 v6, v6, v7
	v_cvt_pk_bf16_f32 v7, v8, v9
	v_cvt_pk_bf16_f32 v8, v2, v3
	v_cvt_pk_bf16_f32 v5, v4, v5
	s_nop 1
	ds_bpermute_b32 v2, v132, v6
	ds_bpermute_b32 v3, v132, v7
	ds_bpermute_b32 v4, v132, v8
	ds_bpermute_b32 v5, v132, v5
	s_waitcnt lgkmcnt(0)
	global_store_dwordx4 v[134:135], v[2:5], off offset:256
	s_mov_b64 s[12:13], -1
	s_cbranch_vccnz .LBB0_223
	s_andn2_b64 vcc, exec, s[2:3]
	s_cbranch_vccnz .LBB0_222
	s_barrier
	s_branch .LBB0_222

; #define GAS __attribute__((address_space(1)))
; __device__ __forceinline__ v4u tr4(int a, v4u x) { return (v4u){bperm(a, x.x), bperm(a, x.y), bperm(a, x.z), bperm(a, x.w)}; }
; __device__ __forceinline__ v4u pack8(const f32x4& a, const f32x4& b) { return (v4u){pg8::cvt_pk_bf16(a[0], a[1]), pg8::cvt_pk_bf16(a[2], a[3]), pg8::cvt_pk_bf16(b[0], b[1]), pg8::cvt_pk_bf16(b[2], b[3])}; }
;     __device__ __forceinline__ bool operator()(AccT& acc, const Unit& u, int wr, int wc, int fr, int fq) const {
;     ...
;         const LaneT t = lane_t(fr, fq);
;         const bf16* src = (const bf16*)(ws + WS_HB); bf16* dst = (bf16*)(ws + WS_YB);
;         const int row0 = u.pm * 256 + wr * 64 + t.tfr, col0 = u.pn * 256 + wc * 32 + 8 * t.tfq;
; #pragma unroll
;         for (int ai = 0; ai < 2; ++ai)
; #pragma unroll
;             for (int m = 0; m < 4; ++m) { const size_t off = (size_t)(row0 + ai * 128 + m * 16) * D + col0;
; #pragma unroll
;                 for (int bj = 0; bj < 2; ++bj) { const v4u r = tr4(t.push, *(const GAS v4u*)(src + off + bj * 128));
;                     const f32x4 y0 = (f32x4){bflo(r.x), bfhi(r.x), bflo(r.y), bfhi(r.y)} * ca + acc[ai][bj][m][0] * cb, y1 = (f32x4){bflo(r.z), bfhi(r.z), bflo(r.w), bfhi(r.w)} * ca + acc[ai][bj][m][1] * cb;
;                     *(GAS v4u*)(dst + off + bj * 128) = tr4(t.pull, pack8(y0, y1)); } }
.LBB0_1828:
	s_mov_b32 s9, s37
	v_mov_b32_e32 v130, v245
	s_mov_b32 s11, s52
	v_mov_b32_e32 v131, v1
	s_lshl_b32 s16, s16, 8
	v_lshl_add_u32 v132, v131, 4, v130
	s_lshl_b32 s9, s9, 6
	v_ashrrev_i32_e32 v134, 2, v132
	v_and_b32_e32 v135, 3, v130
	v_lshlrev_b32_e32 v130, 4, v130
	s_add_i32 s9, s9, s16
	v_lshl_add_u32 v133, v131, 2, v130
	v_add_u32_e32 v130, s9, v134
	s_lshl_b32 s9, s17, 8
	s_lshl_b32 s11, s11, 5
	s_add_i32 s11, s11, s9
	v_and_b32_e32 v132, -4, v132
	v_lshl_or_b32 v134, v135, 3, s11
	v_ashrrev_i32_e32 v131, 31, v130
	v_lshl_add_u32 v132, v135, 6, v132
	v_ashrrev_i32_e32 v135, 31, v134
	v_lshlrev_b64 v[130:131], 10, v[130:131]
	v_lshl_add_u64 v[130:131], v[130:131], 0, v[134:135]
	v_readlane_b32 s18, v253, 11
	v_lshlrev_b64 v[130:131], 1, v[130:131]
	v_readlane_b32 s19, v253, 12
	v_lshl_add_u64 v[140:141], s[60:61], 0, v[130:131]
	s_mov_b64 s[16:17], 0x8000
	v_lshl_add_u64 v[138:139], s[18:19], 0, v[130:131]
	v_mov_b64_e32 v[130:131], v[138:139]
	global_load_dwordx4 v[146:149], v[130:131], off
	s_andn2_b64 vcc, exec, s[6:7]
	global_load_dwordx4 v[150:153], v[130:131], off offset:256
	s_mov_b64 s[16:17], 0x8000
	v_lshl_add_u64 v[130:131], v[138:139], 0, s[16:17]
	global_load_dwordx4 v[154:157], v[130:131], off
	global_load_dwordx4 v[158:161], v[130:131], off offset:256
	s_mov_b64 s[16:17], 0x10000
	v_lshl_add_u64 v[130:131], v[138:139], 0, s[16:17]
	global_load_dwordx4 v[162:165], v[130:131], off
	global_load_dwordx4 v[166:169], v[130:131], off offset:256
	s_mov_b64 s[16:17], 0x18000
	v_lshl_add_u64 v[130:131], v[138:139], 0, s[16:17]
	global_load_dwordx4 v[170:173], v[130:131], off
	global_load_dwordx4 v[174:177], v[130:131], off offset:256
	s_mov_b64 s[16:17], 0x40000
	v_lshl_add_u64 v[130:131], v[138:139], 0, s[16:17]
	global_load_dwordx4 v[178:181], v[130:131], off
	global_load_dwordx4 v[182:185], v[130:131], off offset:256
	s_mov_b64 s[16:17], 0x48000
	v_lshl_add_u64 v[130:131], v[138:139], 0, s[16:17]
	global_load_dwordx4 v[186:189], v[130:131], off
	global_load_dwordx4 v[190:193], v[130:131], off offset:256
	s_waitcnt vmcnt(11)
	ds_bpermute_b32 v143, v133, v147
	ds_bpermute_b32 v142, v133, v146
	ds_bpermute_b32 v145, v133, v149
	ds_bpermute_b32 v144, v133, v148
	v_mov_b64_e32 v[134:135], v[140:141]
	s_waitcnt lgkmcnt(3)
	v_lshlrev_b32_e32 v136, 16, v143
	v_and_b32_e32 v137, 0xffff0000, v143
	s_waitcnt lgkmcnt(2)
	v_and_b32_e32 v143, 0xffff0000, v142
	v_lshlrev_b32_e32 v142, 16, v142
	v_pk_fma_f32 v[128:129], v[136:137], s[96:97], v[128:129] op_sel_hi:[1,0,1]
	v_pk_fma_f32 v[126:127], v[142:143], s[96:97], v[126:127] op_sel_hi:[1,0,1]
	s_waitcnt lgkmcnt(1)
	v_lshlrev_b32_e32 v136, 16, v145
	v_and_b32_e32 v137, 0xffff0000, v145
	s_waitcnt lgkmcnt(0)
	v_and_b32_e32 v145, 0xffff0000, v144
	v_lshlrev_b32_e32 v144, 16, v144
	v_pk_fma_f32 v[124:125], v[136:137], s[96:97], v[124:125] op_sel_hi:[1,0,1]
	v_pk_fma_f32 v[122:123], v[144:145], s[96:97], v[122:123] op_sel_hi:[1,0,1]
	v_cvt_pk_bf16_f32 v126, v126, v127
	v_cvt_pk_bf16_f32 v127, v128, v129
	v_cvt_pk_bf16_f32 v128, v122, v123
	v_cvt_pk_bf16_f32 v125, v124, v125
	s_nop 1
	ds_bpermute_b32 v122, v132, v126
	ds_bpermute_b32 v123, v132, v127
	ds_bpermute_b32 v124, v132, v128
	ds_bpermute_b32 v125, v132, v125
	s_waitcnt lgkmcnt(0)
	global_store_dwordx4 v[134:135], v[122:125], off
	s_mov_b64 s[16:17], 0x50000
	v_lshl_add_u64 v[130:131], v[138:139], 0, s[16:17]
	global_load_dwordx4 v[126:129], v[130:131], off
	s_waitcnt vmcnt(12)
	ds_bpermute_b32 v143, v133, v151
	ds_bpermute_b32 v142, v133, v150
	ds_bpermute_b32 v145, v133, v153
	ds_bpermute_b32 v144, v133, v152
	s_waitcnt lgkmcnt(3)
	v_lshlrev_b32_e32 v136, 16, v143
	v_and_b32_e32 v137, 0xffff0000, v143
	s_waitcnt lgkmcnt(2)
	v_and_b32_e32 v143, 0xffff0000, v142
	v_lshlrev_b32_e32 v142, 16, v142
	v_pk_fma_f32 v[120:121], v[136:137], s[96:97], v[120:121] op_sel_hi:[1,0,1]
	v_pk_fma_f32 v[118:119], v[142:143], s[96:97], v[118:119] op_sel_hi:[1,0,1]
	s_waitcnt lgkmcnt(1)
	v_lshlrev_b32_e32 v136, 16, v145
	v_and_b32_e32 v137, 0xffff0000, v145
	s_waitcnt lgkmcnt(0)
	v_and_b32_e32 v145, 0xffff0000, v144
	v_lshlrev_b32_e32 v144, 16, v144
	v_pk_fma_f32 v[116:117], v[136:137], s[96:97], v[116:117] op_sel_hi:[1,0,1]
	v_pk_fma_f32 v[114:115], v[144:145], s[96:97], v[114:115] op_sel_hi:[1,0,1]
	v_cvt_pk_bf16_f32 v118, v118, v119
	v_cvt_pk_bf16_f32 v119, v120, v121
	v_cvt_pk_bf16_f32 v120, v114, v115
	v_cvt_pk_bf16_f32 v117, v116, v117
	s_nop 1
	ds_bpermute_b32 v114, v132, v118
	ds_bpermute_b32 v115, v132, v119
	ds_bpermute_b32 v116, v132, v120
	ds_bpermute_b32 v117, v132, v117
	s_waitcnt lgkmcnt(0)
	global_store_dwordx4 v[134:135], v[114:117], off offset:256
	global_load_dwordx4 v[118:121], v[130:131], off offset:256
	s_waitcnt vmcnt(13)
	ds_bpermute_b32 v143, v133, v155
	ds_bpermute_b32 v142, v133, v154
	ds_bpermute_b32 v145, v133, v157
	ds_bpermute_b32 v144, v133, v156
	s_mov_b64 s[16:17], 0x8000
	v_lshl_add_u64 v[134:135], v[140:141], 0, s[16:17]
	s_waitcnt lgkmcnt(3)
	v_lshlrev_b32_e32 v136, 16, v143
	v_and_b32_e32 v137, 0xffff0000, v143
	s_waitcnt lgkmcnt(2)
	v_and_b32_e32 v143, 0xffff0000, v142
	v_lshlrev_b32_e32 v142, 16, v142
	v_pk_fma_f32 v[112:113], v[136:137], s[96:97], v[112:113] op_sel_hi:[1,0,1]
	v_pk_fma_f32 v[110:111], v[142:143], s[96:97], v[110:111] op_sel_hi:[1,0,1]
	s_waitcnt lgkmcnt(1)
	v_lshlrev_b32_e32 v136, 16, v145
	v_and_b32_e32 v137, 0xffff0000, v145
	s_waitcnt lgkmcnt(0)
; #define GAS __attribute__((address_space(1)))
; __device__ __forceinline__ v4u tr4(int a, v4u x) { return (v4u){bperm(a, x.x), bperm(a, x.y), bperm(a, x.z), bperm(a, x.w)}; }
; __device__ __forceinline__ v4u pack8(const f32x4& a, const f32x4& b) { return (v4u){pg8::cvt_pk_bf16(a[0], a[1]), pg8::cvt_pk_bf16(a[2], a[3]), pg8::cvt_pk_bf16(b[0], b[1]), pg8::cvt_pk_bf16(b[2], b[3])}; }
;     __device__ __forceinline__ bool operator()(AccT& acc, const Unit& u, int wr, int wc, int fr, int fq) const {
;     ...
;             for (int m = 0; m < 4; ++m) { const size_t off = (size_t)(row0 + ai * 128 + m * 16) * D + col0;
; #pragma unroll
;                 for (int bj = 0; bj < 2; ++bj) { const v4u r = tr4(t.push, *(const GAS v4u*)(src + off + bj * 128));
;                     const f32x4 y0 = (f32x4){bflo(r.x), bfhi(r.x), bflo(r.y), bfhi(r.y)} * ca + acc[ai][bj][m][0] * cb, y1 = (f32x4){bflo(r.z), bfhi(r.z), bflo(r.w), bfhi(r.w)} * ca + acc[ai][bj][m][1] * cb;
;                     *(GAS v4u*)(dst + off + bj * 128) = tr4(t.pull, pack8(y0, y1)); } }
	v_and_b32_e32 v145, 0xffff0000, v144
	v_lshlrev_b32_e32 v144, 16, v144
	v_pk_fma_f32 v[108:109], v[136:137], s[96:97], v[108:109] op_sel_hi:[1,0,1]
	v_pk_fma_f32 v[106:107], v[144:145], s[96:97], v[106:107] op_sel_hi:[1,0,1]
	v_cvt_pk_bf16_f32 v110, v110, v111
	v_cvt_pk_bf16_f32 v111, v112, v113
	v_cvt_pk_bf16_f32 v112, v106, v107
	v_cvt_pk_bf16_f32 v109, v108, v109
	s_nop 1
	ds_bpermute_b32 v106, v132, v110
	ds_bpermute_b32 v107, v132, v111
	ds_bpermute_b32 v108, v132, v112
	ds_bpermute_b32 v109, v132, v109
	s_waitcnt lgkmcnt(0)
	global_store_dwordx4 v[134:135], v[106:109], off
	s_mov_b64 s[16:17], 0x58000
	v_lshl_add_u64 v[130:131], v[138:139], 0, s[16:17]
	global_load_dwordx4 v[110:113], v[130:131], off
	s_waitcnt vmcnt(14)
	ds_bpermute_b32 v143, v133, v159
	ds_bpermute_b32 v142, v133, v158
	ds_bpermute_b32 v145, v133, v161
	ds_bpermute_b32 v144, v133, v160
	s_waitcnt lgkmcnt(3)
	v_lshlrev_b32_e32 v136, 16, v143
	v_and_b32_e32 v137, 0xffff0000, v143
	s_waitcnt lgkmcnt(2)
	v_and_b32_e32 v143, 0xffff0000, v142
	v_lshlrev_b32_e32 v142, 16, v142
	v_pk_fma_f32 v[104:105], v[136:137], s[96:97], v[104:105] op_sel_hi:[1,0,1]
	v_pk_fma_f32 v[102:103], v[142:143], s[96:97], v[102:103] op_sel_hi:[1,0,1]
	s_waitcnt lgkmcnt(1)
	v_lshlrev_b32_e32 v136, 16, v145
	v_and_b32_e32 v137, 0xffff0000, v145
	s_waitcnt lgkmcnt(0)
	v_and_b32_e32 v145, 0xffff0000, v144
	v_lshlrev_b32_e32 v144, 16, v144
	v_pk_fma_f32 v[100:101], v[136:137], s[96:97], v[100:101] op_sel_hi:[1,0,1]
	v_pk_fma_f32 v[98:99], v[144:145], s[96:97], v[98:99] op_sel_hi:[1,0,1]
	v_cvt_pk_bf16_f32 v102, v102, v103
	v_cvt_pk_bf16_f32 v103, v104, v105
	v_cvt_pk_bf16_f32 v104, v98, v99
	v_cvt_pk_bf16_f32 v101, v100, v101
	s_nop 1
	ds_bpermute_b32 v98, v132, v102
	ds_bpermute_b32 v99, v132, v103
	ds_bpermute_b32 v100, v132, v104
	ds_bpermute_b32 v101, v132, v101
	s_waitcnt lgkmcnt(0)
	global_store_dwordx4 v[134:135], v[98:101], off offset:256
	global_load_dwordx4 v[102:105], v[130:131], off offset:256
	s_waitcnt vmcnt(15)
	ds_bpermute_b32 v143, v133, v163
	ds_bpermute_b32 v142, v133, v162
	ds_bpermute_b32 v145, v133, v165
	ds_bpermute_b32 v144, v133, v164
	s_mov_b64 s[16:17], 0x10000
	v_lshl_add_u64 v[134:135], v[140:141], 0, s[16:17]
	s_waitcnt lgkmcnt(3)
	v_lshlrev_b32_e32 v136, 16, v143
	v_and_b32_e32 v137, 0xffff0000, v143
	s_waitcnt lgkmcnt(2)
	v_and_b32_e32 v143, 0xffff0000, v142
	v_lshlrev_b32_e32 v142, 16, v142
	v_pk_fma_f32 v[96:97], v[136:137], s[96:97], v[96:97] op_sel_hi:[1,0,1]
	v_pk_fma_f32 v[94:95], v[142:143], s[96:97], v[94:95] op_sel_hi:[1,0,1]
	s_waitcnt lgkmcnt(1)
	v_lshlrev_b32_e32 v136, 16, v145
	v_and_b32_e32 v137, 0xffff0000, v145
	s_waitcnt lgkmcnt(0)
	v_and_b32_e32 v145, 0xffff0000, v144
	v_lshlrev_b32_e32 v144, 16, v144
	v_pk_fma_f32 v[92:93], v[136:137], s[96:97], v[92:93] op_sel_hi:[1,0,1]
	v_pk_fma_f32 v[90:91], v[144:145], s[96:97], v[90:91] op_sel_hi:[1,0,1]
	v_cvt_pk_bf16_f32 v94, v94, v95
	v_cvt_pk_bf16_f32 v95, v96, v97
	v_cvt_pk_bf16_f32 v96, v90, v91
	v_cvt_pk_bf16_f32 v93, v92, v93
	s_nop 1
	ds_bpermute_b32 v90, v132, v94
	ds_bpermute_b32 v91, v132, v95
	ds_bpermute_b32 v92, v132, v96
	ds_bpermute_b32 v93, v132, v93
	s_waitcnt lgkmcnt(0)
	global_store_dwordx4 v[134:135], v[90:93], off
	s_waitcnt vmcnt(15)
	ds_bpermute_b32 v143, v133, v167
	ds_bpermute_b32 v142, v133, v166
	ds_bpermute_b32 v145, v133, v169
	ds_bpermute_b32 v144, v133, v168
	s_waitcnt lgkmcnt(3)
	v_lshlrev_b32_e32 v136, 16, v143
	v_and_b32_e32 v137, 0xffff0000, v143
	s_waitcnt lgkmcnt(2)
	v_and_b32_e32 v143, 0xffff0000, v142
	v_lshlrev_b32_e32 v142, 16, v142
	v_pk_fma_f32 v[88:89], v[136:137], s[96:97], v[88:89] op_sel_hi:[1,0,1]
	v_pk_fma_f32 v[86:87], v[142:143], s[96:97], v[86:87] op_sel_hi:[1,0,1]
	s_waitcnt lgkmcnt(1)
	v_lshlrev_b32_e32 v136, 16, v145
	v_and_b32_e32 v137, 0xffff0000, v145
	s_waitcnt lgkmcnt(0)
	v_and_b32_e32 v145, 0xffff0000, v144
	v_lshlrev_b32_e32 v144, 16, v144
	v_pk_fma_f32 v[84:85], v[136:137], s[96:97], v[84:85] op_sel_hi:[1,0,1]
	v_pk_fma_f32 v[82:83], v[144:145], s[96:97], v[82:83] op_sel_hi:[1,0,1]
	v_cvt_pk_bf16_f32 v86, v86, v87
	v_cvt_pk_bf16_f32 v87, v88, v89
	v_cvt_pk_bf16_f32 v88, v82, v83
	v_cvt_pk_bf16_f32 v85, v84, v85
	s_nop 1
	ds_bpermute_b32 v82, v132, v86
	ds_bpermute_b32 v83, v132, v87
	ds_bpermute_b32 v84, v132, v88
	ds_bpermute_b32 v85, v132, v85
	s_waitcnt lgkmcnt(0)
	global_store_dwordx4 v[134:135], v[82:85], off offset:256
	s_waitcnt vmcnt(15)
	ds_bpermute_b32 v143, v133, v171
	ds_bpermute_b32 v142, v133, v170
	ds_bpermute_b32 v145, v133, v173
	ds_bpermute_b32 v144, v133, v172
	s_mov_b64 s[16:17], 0x18000
	v_lshl_add_u64 v[134:135], v[140:141], 0, s[16:17]
	s_waitcnt lgkmcnt(3)
	v_lshlrev_b32_e32 v136, 16, v143
	v_and_b32_e32 v137, 0xffff0000, v143
	s_waitcnt lgkmcnt(2)
	v_and_b32_e32 v143, 0xffff0000, v142
	v_lshlrev_b32_e32 v142, 16, v142
	v_pk_fma_f32 v[80:81], v[136:137], s[96:97], v[80:81] op_sel_hi:[1,0,1]
	v_pk_fma_f32 v[78:79], v[142:143], s[96:97], v[78:79] op_sel_hi:[1,0,1]
	s_waitcnt lgkmcnt(1)
	v_lshlrev_b32_e32 v136, 16, v145
	v_and_b32_e32 v137, 0xffff0000, v145
	s_waitcnt lgkmcnt(0)
	v_and_b32_e32 v145, 0xffff0000, v144
	v_lshlrev_b32_e32 v144, 16, v144
	v_pk_fma_f32 v[76:77], v[136:137], s[96:97], v[76:77] op_sel_hi:[1,0,1]
	v_pk_fma_f32 v[74:75], v[144:145], s[96:97], v[74:75] op_sel_hi:[1,0,1]
	v_cvt_pk_bf16_f32 v78, v78, v79
	v_cvt_pk_bf16_f32 v79, v80, v81
	v_cvt_pk_bf16_f32 v80, v74, v75
	v_cvt_pk_bf16_f32 v77, v76, v77
	s_nop 1
	ds_bpermute_b32 v74, v132, v78
	ds_bpermute_b32 v75, v132, v79
	ds_bpermute_b32 v76, v132, v80
	ds_bpermute_b32 v77, v132, v77
	s_waitcnt lgkmcnt(0)
	global_store_dwordx4 v[134:135], v[74:77], off
	s_waitcnt vmcnt(15)
; #define GAS __attribute__((address_space(1)))
; __device__ __forceinline__ v4u tr4(int a, v4u x) { return (v4u){bperm(a, x.x), bperm(a, x.y), bperm(a, x.z), bperm(a, x.w)}; }
; __device__ __forceinline__ v4u pack8(const f32x4& a, const f32x4& b) { return (v4u){pg8::cvt_pk_bf16(a[0], a[1]), pg8::cvt_pk_bf16(a[2], a[3]), pg8::cvt_pk_bf16(b[0], b[1]), pg8::cvt_pk_bf16(b[2], b[3])}; }
;     __device__ __forceinline__ bool operator()(AccT& acc, const Unit& u, int wr, int wc, int fr, int fq) const {
;     ...
;             for (int m = 0; m < 4; ++m) { const size_t off = (size_t)(row0 + ai * 128 + m * 16) * D + col0;
; #pragma unroll
;                 for (int bj = 0; bj < 2; ++bj) { const v4u r = tr4(t.push, *(const GAS v4u*)(src + off + bj * 128));
;                     const f32x4 y0 = (f32x4){bflo(r.x), bfhi(r.x), bflo(r.y), bfhi(r.y)} * ca + acc[ai][bj][m][0] * cb, y1 = (f32x4){bflo(r.z), bfhi(r.z), bflo(r.w), bfhi(r.w)} * ca + acc[ai][bj][m][1] * cb;
;                     *(GAS v4u*)(dst + off + bj * 128) = tr4(t.pull, pack8(y0, y1)); } }
	ds_bpermute_b32 v143, v133, v175
	ds_bpermute_b32 v142, v133, v174
	ds_bpermute_b32 v145, v133, v177
	ds_bpermute_b32 v144, v133, v176
	s_waitcnt lgkmcnt(3)
	v_lshlrev_b32_e32 v136, 16, v143
	v_and_b32_e32 v137, 0xffff0000, v143
	s_waitcnt lgkmcnt(2)
	v_and_b32_e32 v143, 0xffff0000, v142
	v_lshlrev_b32_e32 v142, 16, v142
	v_pk_fma_f32 v[72:73], v[136:137], s[96:97], v[72:73] op_sel_hi:[1,0,1]
	v_pk_fma_f32 v[70:71], v[142:143], s[96:97], v[70:71] op_sel_hi:[1,0,1]
	s_waitcnt lgkmcnt(1)
	v_lshlrev_b32_e32 v136, 16, v145
	v_and_b32_e32 v137, 0xffff0000, v145
	s_waitcnt lgkmcnt(0)
	v_and_b32_e32 v145, 0xffff0000, v144
	v_lshlrev_b32_e32 v144, 16, v144
	v_pk_fma_f32 v[68:69], v[136:137], s[96:97], v[68:69] op_sel_hi:[1,0,1]
	v_pk_fma_f32 v[66:67], v[144:145], s[96:97], v[66:67] op_sel_hi:[1,0,1]
	v_cvt_pk_bf16_f32 v70, v70, v71
	v_cvt_pk_bf16_f32 v71, v72, v73
	v_cvt_pk_bf16_f32 v72, v66, v67
	v_cvt_pk_bf16_f32 v69, v68, v69
	s_nop 1
	ds_bpermute_b32 v66, v132, v70
	ds_bpermute_b32 v67, v132, v71
	ds_bpermute_b32 v68, v132, v72
	ds_bpermute_b32 v69, v132, v69
	s_waitcnt lgkmcnt(0)
	global_store_dwordx4 v[134:135], v[66:69], off offset:256
	s_waitcnt vmcnt(15)
	ds_bpermute_b32 v143, v133, v179
	ds_bpermute_b32 v142, v133, v178
	ds_bpermute_b32 v145, v133, v181
	ds_bpermute_b32 v144, v133, v180
	s_mov_b64 s[16:17], 0x40000
	v_lshl_add_u64 v[134:135], v[140:141], 0, s[16:17]
	s_waitcnt lgkmcnt(3)
	v_lshlrev_b32_e32 v136, 16, v143
	v_and_b32_e32 v137, 0xffff0000, v143
	s_waitcnt lgkmcnt(2)
	v_and_b32_e32 v143, 0xffff0000, v142
	v_lshlrev_b32_e32 v142, 16, v142
	v_pk_fma_f32 v[64:65], v[136:137], s[96:97], v[64:65] op_sel_hi:[1,0,1]
	v_pk_fma_f32 v[62:63], v[142:143], s[96:97], v[62:63] op_sel_hi:[1,0,1]
	s_waitcnt lgkmcnt(1)
	v_lshlrev_b32_e32 v136, 16, v145
	v_and_b32_e32 v137, 0xffff0000, v145
	s_waitcnt lgkmcnt(0)
	v_and_b32_e32 v145, 0xffff0000, v144
	v_lshlrev_b32_e32 v144, 16, v144
	v_pk_fma_f32 v[60:61], v[136:137], s[96:97], v[60:61] op_sel_hi:[1,0,1]
	v_pk_fma_f32 v[58:59], v[144:145], s[96:97], v[58:59] op_sel_hi:[1,0,1]
	v_cvt_pk_bf16_f32 v62, v62, v63
	v_cvt_pk_bf16_f32 v63, v64, v65
	v_cvt_pk_bf16_f32 v64, v58, v59
	v_cvt_pk_bf16_f32 v61, v60, v61
	s_nop 1
	ds_bpermute_b32 v58, v132, v62
	ds_bpermute_b32 v59, v132, v63
	ds_bpermute_b32 v60, v132, v64
	ds_bpermute_b32 v61, v132, v61
	s_waitcnt lgkmcnt(0)
	global_store_dwordx4 v[134:135], v[58:61], off
	s_waitcnt vmcnt(15)
	ds_bpermute_b32 v143, v133, v183
	ds_bpermute_b32 v142, v133, v182
	ds_bpermute_b32 v145, v133, v185
	ds_bpermute_b32 v144, v133, v184
	s_waitcnt lgkmcnt(3)
	v_lshlrev_b32_e32 v136, 16, v143
	v_and_b32_e32 v137, 0xffff0000, v143
	s_waitcnt lgkmcnt(2)
	v_and_b32_e32 v143, 0xffff0000, v142
	v_lshlrev_b32_e32 v142, 16, v142
	v_pk_fma_f32 v[56:57], v[136:137], s[96:97], v[56:57] op_sel_hi:[1,0,1]
	v_pk_fma_f32 v[54:55], v[142:143], s[96:97], v[54:55] op_sel_hi:[1,0,1]
	s_waitcnt lgkmcnt(1)
	v_lshlrev_b32_e32 v136, 16, v145
	v_and_b32_e32 v137, 0xffff0000, v145
	s_waitcnt lgkmcnt(0)
	v_and_b32_e32 v145, 0xffff0000, v144
	v_lshlrev_b32_e32 v144, 16, v144
	v_pk_fma_f32 v[52:53], v[136:137], s[96:97], v[52:53] op_sel_hi:[1,0,1]
	v_pk_fma_f32 v[50:51], v[144:145], s[96:97], v[50:51] op_sel_hi:[1,0,1]
	v_cvt_pk_bf16_f32 v54, v54, v55
	v_cvt_pk_bf16_f32 v55, v56, v57
	v_cvt_pk_bf16_f32 v56, v50, v51
	v_cvt_pk_bf16_f32 v53, v52, v53
	s_nop 1
	ds_bpermute_b32 v50, v132, v54
	ds_bpermute_b32 v51, v132, v55
	ds_bpermute_b32 v52, v132, v56
	ds_bpermute_b32 v53, v132, v53
	s_waitcnt lgkmcnt(0)
	global_store_dwordx4 v[134:135], v[50:53], off offset:256
	s_waitcnt vmcnt(15)
	ds_bpermute_b32 v143, v133, v187
	ds_bpermute_b32 v142, v133, v186
	ds_bpermute_b32 v145, v133, v189
	ds_bpermute_b32 v144, v133, v188
	s_mov_b64 s[16:17], 0x48000
	v_lshl_add_u64 v[134:135], v[140:141], 0, s[16:17]
	s_waitcnt lgkmcnt(3)
	v_lshlrev_b32_e32 v136, 16, v143
	v_and_b32_e32 v137, 0xffff0000, v143
	s_waitcnt lgkmcnt(2)
	v_and_b32_e32 v143, 0xffff0000, v142
	v_lshlrev_b32_e32 v142, 16, v142
	v_pk_fma_f32 v[48:49], v[136:137], s[96:97], v[48:49] op_sel_hi:[1,0,1]
	v_pk_fma_f32 v[46:47], v[142:143], s[96:97], v[46:47] op_sel_hi:[1,0,1]
	s_waitcnt lgkmcnt(1)
	v_lshlrev_b32_e32 v136, 16, v145
	v_and_b32_e32 v137, 0xffff0000, v145
	s_waitcnt lgkmcnt(0)
	v_and_b32_e32 v145, 0xffff0000, v144
	v_lshlrev_b32_e32 v144, 16, v144
	v_pk_fma_f32 v[44:45], v[136:137], s[96:97], v[44:45] op_sel_hi:[1,0,1]
	v_pk_fma_f32 v[42:43], v[144:145], s[96:97], v[42:43] op_sel_hi:[1,0,1]
	v_cvt_pk_bf16_f32 v46, v46, v47
	v_cvt_pk_bf16_f32 v47, v48, v49
	v_cvt_pk_bf16_f32 v48, v42, v43
	v_cvt_pk_bf16_f32 v45, v44, v45
	s_nop 1
	ds_bpermute_b32 v42, v132, v46
	ds_bpermute_b32 v43, v132, v47
	ds_bpermute_b32 v44, v132, v48
	ds_bpermute_b32 v45, v132, v45
	s_waitcnt lgkmcnt(0)
	global_store_dwordx4 v[134:135], v[42:45], off
	s_waitcnt vmcnt(15)
	ds_bpermute_b32 v143, v133, v191
	ds_bpermute_b32 v142, v133, v190
	ds_bpermute_b32 v145, v133, v193
	ds_bpermute_b32 v144, v133, v192
	s_waitcnt lgkmcnt(3)
	v_lshlrev_b32_e32 v136, 16, v143
	v_and_b32_e32 v137, 0xffff0000, v143
	s_waitcnt lgkmcnt(2)
	v_and_b32_e32 v143, 0xffff0000, v142
	v_lshlrev_b32_e32 v142, 16, v142
	v_pk_fma_f32 v[40:41], v[136:137], s[96:97], v[40:41] op_sel_hi:[1,0,1]
	v_pk_fma_f32 v[38:39], v[142:143], s[96:97], v[38:39] op_sel_hi:[1,0,1]
	s_waitcnt lgkmcnt(1)
	v_lshlrev_b32_e32 v136, 16, v145
	v_and_b32_e32 v137, 0xffff0000, v145
	s_waitcnt lgkmcnt(0)
; #define GAS __attribute__((address_space(1)))
; __device__ __forceinline__ v4u tr4(int a, v4u x) { return (v4u){bperm(a, x.x), bperm(a, x.y), bperm(a, x.z), bperm(a, x.w)}; }
; __device__ __forceinline__ v4u pack8(const f32x4& a, const f32x4& b) { return (v4u){pg8::cvt_pk_bf16(a[0], a[1]), pg8::cvt_pk_bf16(a[2], a[3]), pg8::cvt_pk_bf16(b[0], b[1]), pg8::cvt_pk_bf16(b[2], b[3])}; }
;     __device__ __forceinline__ bool operator()(AccT& acc, const Unit& u, int wr, int wc, int fr, int fq) const {
;     ...
;             for (int m = 0; m < 4; ++m) { const size_t off = (size_t)(row0 + ai * 128 + m * 16) * D + col0;
; #pragma unroll
;                 for (int bj = 0; bj < 2; ++bj) { const v4u r = tr4(t.push, *(const GAS v4u*)(src + off + bj * 128));
;                     const f32x4 y0 = (f32x4){bflo(r.x), bfhi(r.x), bflo(r.y), bfhi(r.y)} * ca + acc[ai][bj][m][0] * cb, y1 = (f32x4){bflo(r.z), bfhi(r.z), bflo(r.w), bfhi(r.w)} * ca + acc[ai][bj][m][1] * cb;
;                     *(GAS v4u*)(dst + off + bj * 128) = tr4(t.pull, pack8(y0, y1)); } }
	v_and_b32_e32 v145, 0xffff0000, v144
	v_lshlrev_b32_e32 v144, 16, v144
	v_pk_fma_f32 v[36:37], v[136:137], s[96:97], v[36:37] op_sel_hi:[1,0,1]
	v_pk_fma_f32 v[34:35], v[144:145], s[96:97], v[34:35] op_sel_hi:[1,0,1]
	v_cvt_pk_bf16_f32 v38, v38, v39
	v_cvt_pk_bf16_f32 v39, v40, v41
	v_cvt_pk_bf16_f32 v40, v34, v35
	v_cvt_pk_bf16_f32 v37, v36, v37
	s_nop 1
	ds_bpermute_b32 v34, v132, v38
	ds_bpermute_b32 v35, v132, v39
	ds_bpermute_b32 v36, v132, v40
	ds_bpermute_b32 v37, v132, v37
	s_waitcnt lgkmcnt(0)
	global_store_dwordx4 v[134:135], v[34:37], off offset:256
	s_waitcnt vmcnt(14)
	ds_bpermute_b32 v143, v133, v127
	ds_bpermute_b32 v142, v133, v126
	ds_bpermute_b32 v145, v133, v129
	ds_bpermute_b32 v144, v133, v128
	s_mov_b64 s[16:17], 0x50000
	v_lshl_add_u64 v[134:135], v[140:141], 0, s[16:17]
	s_waitcnt lgkmcnt(3)
	v_lshlrev_b32_e32 v136, 16, v143
	v_and_b32_e32 v137, 0xffff0000, v143
	s_waitcnt lgkmcnt(2)
	v_and_b32_e32 v143, 0xffff0000, v142
	v_lshlrev_b32_e32 v142, 16, v142
	v_pk_fma_f32 v[32:33], v[136:137], s[96:97], v[32:33] op_sel_hi:[1,0,1]
	v_pk_fma_f32 v[30:31], v[142:143], s[96:97], v[30:31] op_sel_hi:[1,0,1]
	s_waitcnt lgkmcnt(1)
	v_lshlrev_b32_e32 v136, 16, v145
	v_and_b32_e32 v137, 0xffff0000, v145
	s_waitcnt lgkmcnt(0)
	v_and_b32_e32 v145, 0xffff0000, v144
	v_lshlrev_b32_e32 v144, 16, v144
	v_pk_fma_f32 v[28:29], v[136:137], s[96:97], v[28:29] op_sel_hi:[1,0,1]
	v_pk_fma_f32 v[26:27], v[144:145], s[96:97], v[26:27] op_sel_hi:[1,0,1]
	v_cvt_pk_bf16_f32 v30, v30, v31
	v_cvt_pk_bf16_f32 v31, v32, v33
	v_cvt_pk_bf16_f32 v32, v26, v27
	v_cvt_pk_bf16_f32 v29, v28, v29
	s_nop 1
	ds_bpermute_b32 v26, v132, v30
	ds_bpermute_b32 v27, v132, v31
	ds_bpermute_b32 v28, v132, v32
	ds_bpermute_b32 v29, v132, v29
	s_waitcnt lgkmcnt(0)
	global_store_dwordx4 v[134:135], v[26:29], off
	s_waitcnt vmcnt(13)
	ds_bpermute_b32 v143, v133, v119
	ds_bpermute_b32 v142, v133, v118
	ds_bpermute_b32 v145, v133, v121
	ds_bpermute_b32 v144, v133, v120
	s_waitcnt lgkmcnt(3)
	v_lshlrev_b32_e32 v136, 16, v143
	v_and_b32_e32 v137, 0xffff0000, v143
	s_waitcnt lgkmcnt(2)
	v_and_b32_e32 v143, 0xffff0000, v142
	v_lshlrev_b32_e32 v142, 16, v142
	v_pk_fma_f32 v[24:25], v[136:137], s[96:97], v[24:25] op_sel_hi:[1,0,1]
	v_pk_fma_f32 v[22:23], v[142:143], s[96:97], v[22:23] op_sel_hi:[1,0,1]
	s_waitcnt lgkmcnt(1)
	v_lshlrev_b32_e32 v136, 16, v145
	v_and_b32_e32 v137, 0xffff0000, v145
	s_waitcnt lgkmcnt(0)
	v_and_b32_e32 v145, 0xffff0000, v144
	v_lshlrev_b32_e32 v144, 16, v144
	v_pk_fma_f32 v[20:21], v[136:137], s[96:97], v[20:21] op_sel_hi:[1,0,1]
	v_pk_fma_f32 v[18:19], v[144:145], s[96:97], v[18:19] op_sel_hi:[1,0,1]
	v_cvt_pk_bf16_f32 v22, v22, v23
	v_cvt_pk_bf16_f32 v23, v24, v25
	v_cvt_pk_bf16_f32 v24, v18, v19
	v_cvt_pk_bf16_f32 v21, v20, v21
	s_nop 1
	ds_bpermute_b32 v18, v132, v22
	ds_bpermute_b32 v19, v132, v23
	ds_bpermute_b32 v20, v132, v24
	ds_bpermute_b32 v21, v132, v21
	s_waitcnt lgkmcnt(0)
	global_store_dwordx4 v[134:135], v[18:21], off offset:256
	s_waitcnt vmcnt(12)
	ds_bpermute_b32 v143, v133, v111
	ds_bpermute_b32 v142, v133, v110
	ds_bpermute_b32 v145, v133, v113
	ds_bpermute_b32 v144, v133, v112
	s_mov_b64 s[16:17], 0x58000
	v_lshl_add_u64 v[134:135], v[140:141], 0, s[16:17]
	s_waitcnt lgkmcnt(3)
	v_lshlrev_b32_e32 v136, 16, v143
	v_and_b32_e32 v137, 0xffff0000, v143
	s_waitcnt lgkmcnt(2)
	v_and_b32_e32 v143, 0xffff0000, v142
	v_lshlrev_b32_e32 v142, 16, v142
	v_pk_fma_f32 v[16:17], v[136:137], s[96:97], v[16:17] op_sel_hi:[1,0,1]
	v_pk_fma_f32 v[14:15], v[142:143], s[96:97], v[14:15] op_sel_hi:[1,0,1]
	s_waitcnt lgkmcnt(1)
	v_lshlrev_b32_e32 v136, 16, v145
	v_and_b32_e32 v137, 0xffff0000, v145
	s_waitcnt lgkmcnt(0)
	v_and_b32_e32 v145, 0xffff0000, v144
	v_lshlrev_b32_e32 v144, 16, v144
	v_pk_fma_f32 v[12:13], v[136:137], s[96:97], v[12:13] op_sel_hi:[1,0,1]
	v_pk_fma_f32 v[10:11], v[144:145], s[96:97], v[10:11] op_sel_hi:[1,0,1]
	v_cvt_pk_bf16_f32 v14, v14, v15
	v_cvt_pk_bf16_f32 v15, v16, v17
	v_cvt_pk_bf16_f32 v16, v10, v11
	v_cvt_pk_bf16_f32 v13, v12, v13
	s_nop 1
	ds_bpermute_b32 v10, v132, v14
	ds_bpermute_b32 v11, v132, v15
	ds_bpermute_b32 v12, v132, v16
	ds_bpermute_b32 v13, v132, v13
	s_waitcnt lgkmcnt(0)
	global_store_dwordx4 v[134:135], v[10:13], off
	s_waitcnt vmcnt(11)
	ds_bpermute_b32 v143, v133, v103
	ds_bpermute_b32 v142, v133, v102
	ds_bpermute_b32 v145, v133, v105
	ds_bpermute_b32 v144, v133, v104
	s_waitcnt lgkmcnt(3)
	v_lshlrev_b32_e32 v136, 16, v143
	v_and_b32_e32 v137, 0xffff0000, v143
	s_waitcnt lgkmcnt(2)
	v_and_b32_e32 v143, 0xffff0000, v142
	v_lshlrev_b32_e32 v142, 16, v142
	v_pk_fma_f32 v[8:9], v[136:137], s[96:97], v[8:9] op_sel_hi:[1,0,1]
	v_pk_fma_f32 v[6:7], v[142:143], s[96:97], v[6:7] op_sel_hi:[1,0,1]
	s_waitcnt lgkmcnt(1)
	v_lshlrev_b32_e32 v136, 16, v145
	v_and_b32_e32 v137, 0xffff0000, v145
	s_waitcnt lgkmcnt(0)
	v_and_b32_e32 v145, 0xffff0000, v144
	v_lshlrev_b32_e32 v144, 16, v144
	v_pk_fma_f32 v[4:5], v[136:137], s[96:97], v[4:5] op_sel_hi:[1,0,1]
	v_pk_fma_f32 v[2:3], v[144:145], s[96:97], v[2:3] op_sel_hi:[1,0,1]
	v_cvt_pk_bf16_f32 v6, v6, v7
	v_cvt_pk_bf16_f32 v7, v8, v9
	v_cvt_pk_bf16_f32 v8, v2, v3
	v_cvt_pk_bf16_f32 v5, v4, v5
	s_nop 1
	ds_bpermute_b32 v2, v132, v6
	ds_bpermute_b32 v3, v132, v7
	ds_bpermute_b32 v4, v132, v8
	ds_bpermute_b32 v5, v132, v5
	s_waitcnt lgkmcnt(0)
	global_store_dwordx4 v[134:135], v[2:5], off offset:256
	s_mov_b64 s[16:17], -1
	s_cbranch_vccnz .LBB0_1813
	s_andn2_b64 vcc, exec, s[2:3]
	s_cbranch_vccnz .LBB0_1812
	s_barrier
	s_branch .LBB0_1812

; #define GAS __attribute__((address_space(1)))
; __device__ __forceinline__ v4u tr4(int a, v4u x) { return (v4u){bperm(a, x.x), bperm(a, x.y), bperm(a, x.z), bperm(a, x.w)}; }
; __device__ __forceinline__ v4u pack8(const f32x4& a, const f32x4& b) { return (v4u){pg8::cvt_pk_bf16(a[0], a[1]), pg8::cvt_pk_bf16(a[2], a[3]), pg8::cvt_pk_bf16(b[0], b[1]), pg8::cvt_pk_bf16(b[2], b[3])}; }
;     __device__ __forceinline__ bool operator()(AccT& acc, const Unit& u, int wr, int wc, int fr, int fq) const {
;     ...
;         const LaneT t = lane_t(fr, fq);
;         const bf16* src = (const bf16*)(ws + WS_HB); bf16* dst = (bf16*)(ws + WS_YB);
;         const int row0 = u.pm * 256 + wr * 64 + t.tfr, col0 = u.pn * 256 + wc * 32 + 8 * t.tfq;
; #pragma unroll
;         for (int ai = 0; ai < 2; ++ai)
; #pragma unroll
;             for (int m = 0; m < 4; ++m) { const size_t off = (size_t)(row0 + ai * 128 + m * 16) * D + col0;
; #pragma unroll
;                 for (int bj = 0; bj < 2; ++bj) { const v4u r = tr4(t.push, *(const GAS v4u*)(src + off + bj * 128));
;                     const f32x4 y0 = (f32x4){bflo(r.x), bfhi(r.x), bflo(r.y), bfhi(r.y)} * ca + acc[ai][bj][m][0] * cb, y1 = (f32x4){bflo(r.z), bfhi(r.z), bflo(r.w), bfhi(r.w)} * ca + acc[ai][bj][m][1] * cb;
;                     *(GAS v4u*)(dst + off + bj * 128) = tr4(t.pull, pack8(y0, y1)); } }
.LBB0_2037:
	s_mov_b32 s12, s41
	v_mov_b32_e32 v130, v1
	s_mov_b32 s13, s29
	v_mov_b32_e32 v131, v245
	s_lshl_b32 s14, s54, 8
	v_lshl_add_u32 v132, v130, 4, v131
	s_lshl_b32 s13, s13, 6
	v_ashrrev_i32_e32 v134, 2, v132
	v_and_b32_e32 v135, 3, v131
	v_lshlrev_b32_e32 v131, 4, v131
	s_add_i32 s13, s13, s14
	v_lshl_add_u32 v133, v130, 2, v131
	v_add_u32_e32 v130, s13, v134
	s_lshl_b32 s13, s56, 8
	s_lshl_b32 s12, s12, 5
	s_add_i32 s12, s12, s13
	v_and_b32_e32 v132, -4, v132
	v_lshl_or_b32 v134, v135, 3, s12
	v_ashrrev_i32_e32 v131, 31, v130
	v_lshl_add_u32 v132, v135, 6, v132
	v_ashrrev_i32_e32 v135, 31, v134
	v_lshlrev_b64 v[130:131], 10, v[130:131]
	v_lshl_add_u64 v[130:131], v[130:131], 0, v[134:135]
	v_readlane_b32 s14, v253, 11
	v_lshlrev_b64 v[130:131], 1, v[130:131]
	v_readlane_b32 s15, v253, 12
	v_lshl_add_u64 v[140:141], s[60:61], 0, v[130:131]
	s_mov_b64 s[12:13], 0x8000
	v_lshl_add_u64 v[138:139], s[14:15], 0, v[130:131]
	v_mov_b64_e32 v[130:131], v[138:139]
	global_load_dwordx4 v[146:149], v[130:131], off
	s_and_b64 vcc, exec, s[6:7]
	global_load_dwordx4 v[150:153], v[130:131], off offset:256
	s_mov_b64 s[12:13], 0x8000
	v_lshl_add_u64 v[130:131], v[138:139], 0, s[12:13]
	global_load_dwordx4 v[154:157], v[130:131], off
	global_load_dwordx4 v[158:161], v[130:131], off offset:256
	s_mov_b64 s[12:13], 0x10000
	v_lshl_add_u64 v[130:131], v[138:139], 0, s[12:13]
	global_load_dwordx4 v[162:165], v[130:131], off
	global_load_dwordx4 v[166:169], v[130:131], off offset:256
	s_mov_b64 s[12:13], 0x18000
	v_lshl_add_u64 v[130:131], v[138:139], 0, s[12:13]
	global_load_dwordx4 v[170:173], v[130:131], off
	global_load_dwordx4 v[174:177], v[130:131], off offset:256
	s_mov_b64 s[12:13], 0x40000
	v_lshl_add_u64 v[130:131], v[138:139], 0, s[12:13]
	global_load_dwordx4 v[178:181], v[130:131], off
	global_load_dwordx4 v[182:185], v[130:131], off offset:256
	s_mov_b64 s[12:13], 0x48000
	v_lshl_add_u64 v[130:131], v[138:139], 0, s[12:13]
	global_load_dwordx4 v[186:189], v[130:131], off
	global_load_dwordx4 v[190:193], v[130:131], off offset:256
	s_waitcnt vmcnt(11)
	ds_bpermute_b32 v143, v133, v147
	ds_bpermute_b32 v142, v133, v146
	ds_bpermute_b32 v145, v133, v149
	ds_bpermute_b32 v144, v133, v148
	v_mov_b64_e32 v[134:135], v[140:141]
	s_waitcnt lgkmcnt(3)
	v_lshlrev_b32_e32 v136, 16, v143
	v_and_b32_e32 v137, 0xffff0000, v143
	s_waitcnt lgkmcnt(2)
	v_and_b32_e32 v143, 0xffff0000, v142
	v_lshlrev_b32_e32 v142, 16, v142
	v_pk_mul_f32 v[136:137], v[136:137], s[96:97] op_sel_hi:[1,0]
	v_pk_fma_f32 v[128:129], v[128:129], 0.5, v[136:137] op_sel_hi:[1,0,1]
	v_pk_mul_f32 v[142:143], v[142:143], s[96:97] op_sel_hi:[1,0]
	v_pk_fma_f32 v[126:127], v[126:127], 0.5, v[142:143] op_sel_hi:[1,0,1]
	s_waitcnt lgkmcnt(1)
	v_lshlrev_b32_e32 v136, 16, v145
	v_and_b32_e32 v137, 0xffff0000, v145
	s_waitcnt lgkmcnt(0)
	v_and_b32_e32 v145, 0xffff0000, v144
	v_lshlrev_b32_e32 v144, 16, v144
	v_pk_mul_f32 v[136:137], v[136:137], s[96:97] op_sel_hi:[1,0]
	v_pk_fma_f32 v[124:125], v[124:125], 0.5, v[136:137] op_sel_hi:[1,0,1]
	v_pk_mul_f32 v[144:145], v[144:145], s[96:97] op_sel_hi:[1,0]
	v_pk_fma_f32 v[122:123], v[122:123], 0.5, v[144:145] op_sel_hi:[1,0,1]
	v_cvt_pk_bf16_f32 v126, v126, v127
	v_cvt_pk_bf16_f32 v127, v128, v129
	v_cvt_pk_bf16_f32 v128, v122, v123
	v_cvt_pk_bf16_f32 v125, v124, v125
	s_nop 1
	ds_bpermute_b32 v122, v132, v126
	ds_bpermute_b32 v123, v132, v127
	ds_bpermute_b32 v124, v132, v128
	ds_bpermute_b32 v125, v132, v125
	s_waitcnt lgkmcnt(0)
	global_store_dwordx4 v[134:135], v[122:125], off
	s_mov_b64 s[12:13], 0x50000
	v_lshl_add_u64 v[130:131], v[138:139], 0, s[12:13]
	global_load_dwordx4 v[126:129], v[130:131], off
	s_waitcnt vmcnt(12)
	ds_bpermute_b32 v143, v133, v151
	ds_bpermute_b32 v142, v133, v150
	ds_bpermute_b32 v145, v133, v153
	ds_bpermute_b32 v144, v133, v152
	s_waitcnt lgkmcnt(3)
	v_lshlrev_b32_e32 v136, 16, v143
	v_and_b32_e32 v137, 0xffff0000, v143
	s_waitcnt lgkmcnt(2)
	v_and_b32_e32 v143, 0xffff0000, v142
	v_lshlrev_b32_e32 v142, 16, v142
	v_pk_mul_f32 v[136:137], v[136:137], s[96:97] op_sel_hi:[1,0]
	v_pk_fma_f32 v[120:121], v[120:121], 0.5, v[136:137] op_sel_hi:[1,0,1]
	v_pk_mul_f32 v[142:143], v[142:143], s[96:97] op_sel_hi:[1,0]
	v_pk_fma_f32 v[118:119], v[118:119], 0.5, v[142:143] op_sel_hi:[1,0,1]
	s_waitcnt lgkmcnt(1)
	v_lshlrev_b32_e32 v136, 16, v145
	v_and_b32_e32 v137, 0xffff0000, v145
	s_waitcnt lgkmcnt(0)
	v_and_b32_e32 v145, 0xffff0000, v144
	v_lshlrev_b32_e32 v144, 16, v144
	v_pk_mul_f32 v[136:137], v[136:137], s[96:97] op_sel_hi:[1,0]
	v_pk_fma_f32 v[116:117], v[116:117], 0.5, v[136:137] op_sel_hi:[1,0,1]
	v_pk_mul_f32 v[144:145], v[144:145], s[96:97] op_sel_hi:[1,0]
	v_pk_fma_f32 v[114:115], v[114:115], 0.5, v[144:145] op_sel_hi:[1,0,1]
	v_cvt_pk_bf16_f32 v118, v118, v119
	v_cvt_pk_bf16_f32 v119, v120, v121
	v_cvt_pk_bf16_f32 v120, v114, v115
	v_cvt_pk_bf16_f32 v117, v116, v117
	s_nop 1
	ds_bpermute_b32 v114, v132, v118
	ds_bpermute_b32 v115, v132, v119
	ds_bpermute_b32 v116, v132, v120
	ds_bpermute_b32 v117, v132, v117
	s_waitcnt lgkmcnt(0)
	global_store_dwordx4 v[134:135], v[114:117], off offset:256
	global_load_dwordx4 v[118:121], v[130:131], off offset:256
	s_waitcnt vmcnt(13)
	ds_bpermute_b32 v143, v133, v155
	ds_bpermute_b32 v142, v133, v154
	ds_bpermute_b32 v145, v133, v157
	ds_bpermute_b32 v144, v133, v156
	s_mov_b64 s[12:13], 0x8000
	v_lshl_add_u64 v[134:135], v[140:141], 0, s[12:13]
	s_waitcnt lgkmcnt(3)
	v_lshlrev_b32_e32 v136, 16, v143
	v_and_b32_e32 v137, 0xffff0000, v143
	s_waitcnt lgkmcnt(2)
; #define GAS __attribute__((address_space(1)))
; __device__ __forceinline__ v4u tr4(int a, v4u x) { return (v4u){bperm(a, x.x), bperm(a, x.y), bperm(a, x.z), bperm(a, x.w)}; }
; __device__ __forceinline__ v4u pack8(const f32x4& a, const f32x4& b) { return (v4u){pg8::cvt_pk_bf16(a[0], a[1]), pg8::cvt_pk_bf16(a[2], a[3]), pg8::cvt_pk_bf16(b[0], b[1]), pg8::cvt_pk_bf16(b[2], b[3])}; }
;     __device__ __forceinline__ bool operator()(AccT& acc, const Unit& u, int wr, int wc, int fr, int fq) const {
;     ...
;             for (int m = 0; m < 4; ++m) { const size_t off = (size_t)(row0 + ai * 128 + m * 16) * D + col0;
; #pragma unroll
;                 for (int bj = 0; bj < 2; ++bj) { const v4u r = tr4(t.push, *(const GAS v4u*)(src + off + bj * 128));
;                     const f32x4 y0 = (f32x4){bflo(r.x), bfhi(r.x), bflo(r.y), bfhi(r.y)} * ca + acc[ai][bj][m][0] * cb, y1 = (f32x4){bflo(r.z), bfhi(r.z), bflo(r.w), bfhi(r.w)} * ca + acc[ai][bj][m][1] * cb;
;                     *(GAS v4u*)(dst + off + bj * 128) = tr4(t.pull, pack8(y0, y1)); } }
	v_and_b32_e32 v143, 0xffff0000, v142
	v_lshlrev_b32_e32 v142, 16, v142
	v_pk_mul_f32 v[136:137], v[136:137], s[96:97] op_sel_hi:[1,0]
	v_pk_fma_f32 v[112:113], v[112:113], 0.5, v[136:137] op_sel_hi:[1,0,1]
	v_pk_mul_f32 v[142:143], v[142:143], s[96:97] op_sel_hi:[1,0]
	v_pk_fma_f32 v[110:111], v[110:111], 0.5, v[142:143] op_sel_hi:[1,0,1]
	s_waitcnt lgkmcnt(1)
	v_lshlrev_b32_e32 v136, 16, v145
	v_and_b32_e32 v137, 0xffff0000, v145
	s_waitcnt lgkmcnt(0)
	v_and_b32_e32 v145, 0xffff0000, v144
	v_lshlrev_b32_e32 v144, 16, v144
	v_pk_mul_f32 v[136:137], v[136:137], s[96:97] op_sel_hi:[1,0]
	v_pk_fma_f32 v[108:109], v[108:109], 0.5, v[136:137] op_sel_hi:[1,0,1]
	v_pk_mul_f32 v[144:145], v[144:145], s[96:97] op_sel_hi:[1,0]
	v_pk_fma_f32 v[106:107], v[106:107], 0.5, v[144:145] op_sel_hi:[1,0,1]
	v_cvt_pk_bf16_f32 v110, v110, v111
	v_cvt_pk_bf16_f32 v111, v112, v113
	v_cvt_pk_bf16_f32 v112, v106, v107
	v_cvt_pk_bf16_f32 v109, v108, v109
	s_nop 1
	ds_bpermute_b32 v106, v132, v110
	ds_bpermute_b32 v107, v132, v111
	ds_bpermute_b32 v108, v132, v112
	ds_bpermute_b32 v109, v132, v109
	s_waitcnt lgkmcnt(0)
	global_store_dwordx4 v[134:135], v[106:109], off
	s_mov_b64 s[12:13], 0x58000
	v_lshl_add_u64 v[130:131], v[138:139], 0, s[12:13]
	global_load_dwordx4 v[110:113], v[130:131], off
	s_waitcnt vmcnt(14)
	ds_bpermute_b32 v143, v133, v159
	ds_bpermute_b32 v142, v133, v158
	ds_bpermute_b32 v145, v133, v161
	ds_bpermute_b32 v144, v133, v160
	s_waitcnt lgkmcnt(3)
	v_lshlrev_b32_e32 v136, 16, v143
	v_and_b32_e32 v137, 0xffff0000, v143
	s_waitcnt lgkmcnt(2)
	v_and_b32_e32 v143, 0xffff0000, v142
	v_lshlrev_b32_e32 v142, 16, v142
	v_pk_mul_f32 v[136:137], v[136:137], s[96:97] op_sel_hi:[1,0]
	v_pk_fma_f32 v[104:105], v[104:105], 0.5, v[136:137] op_sel_hi:[1,0,1]
	v_pk_mul_f32 v[142:143], v[142:143], s[96:97] op_sel_hi:[1,0]
	v_pk_fma_f32 v[102:103], v[102:103], 0.5, v[142:143] op_sel_hi:[1,0,1]
	s_waitcnt lgkmcnt(1)
	v_lshlrev_b32_e32 v136, 16, v145
	v_and_b32_e32 v137, 0xffff0000, v145
	s_waitcnt lgkmcnt(0)
	v_and_b32_e32 v145, 0xffff0000, v144
	v_lshlrev_b32_e32 v144, 16, v144
	v_pk_mul_f32 v[136:137], v[136:137], s[96:97] op_sel_hi:[1,0]
	v_pk_fma_f32 v[100:101], v[100:101], 0.5, v[136:137] op_sel_hi:[1,0,1]
	v_pk_mul_f32 v[144:145], v[144:145], s[96:97] op_sel_hi:[1,0]
	v_pk_fma_f32 v[98:99], v[98:99], 0.5, v[144:145] op_sel_hi:[1,0,1]
	v_cvt_pk_bf16_f32 v102, v102, v103
	v_cvt_pk_bf16_f32 v103, v104, v105
	v_cvt_pk_bf16_f32 v104, v98, v99
	v_cvt_pk_bf16_f32 v101, v100, v101
	s_nop 1
	ds_bpermute_b32 v98, v132, v102
	ds_bpermute_b32 v99, v132, v103
	ds_bpermute_b32 v100, v132, v104
	ds_bpermute_b32 v101, v132, v101
	s_waitcnt lgkmcnt(0)
	global_store_dwordx4 v[134:135], v[98:101], off offset:256
	global_load_dwordx4 v[102:105], v[130:131], off offset:256
	s_waitcnt vmcnt(15)
	ds_bpermute_b32 v143, v133, v163
	ds_bpermute_b32 v142, v133, v162
	ds_bpermute_b32 v145, v133, v165
	ds_bpermute_b32 v144, v133, v164
	s_mov_b64 s[12:13], 0x10000
	v_lshl_add_u64 v[134:135], v[140:141], 0, s[12:13]
	s_waitcnt lgkmcnt(3)
	v_lshlrev_b32_e32 v136, 16, v143
	v_and_b32_e32 v137, 0xffff0000, v143
	s_waitcnt lgkmcnt(2)
	v_and_b32_e32 v143, 0xffff0000, v142
	v_lshlrev_b32_e32 v142, 16, v142
	v_pk_mul_f32 v[136:137], v[136:137], s[96:97] op_sel_hi:[1,0]
	v_pk_fma_f32 v[96:97], v[96:97], 0.5, v[136:137] op_sel_hi:[1,0,1]
	v_pk_mul_f32 v[142:143], v[142:143], s[96:97] op_sel_hi:[1,0]
	v_pk_fma_f32 v[94:95], v[94:95], 0.5, v[142:143] op_sel_hi:[1,0,1]
	s_waitcnt lgkmcnt(1)
	v_lshlrev_b32_e32 v136, 16, v145
	v_and_b32_e32 v137, 0xffff0000, v145
	s_waitcnt lgkmcnt(0)
	v_and_b32_e32 v145, 0xffff0000, v144
	v_lshlrev_b32_e32 v144, 16, v144
	v_pk_mul_f32 v[136:137], v[136:137], s[96:97] op_sel_hi:[1,0]
	v_pk_fma_f32 v[92:93], v[92:93], 0.5, v[136:137] op_sel_hi:[1,0,1]
	v_pk_mul_f32 v[144:145], v[144:145], s[96:97] op_sel_hi:[1,0]
	v_pk_fma_f32 v[90:91], v[90:91], 0.5, v[144:145] op_sel_hi:[1,0,1]
	v_cvt_pk_bf16_f32 v94, v94, v95
	v_cvt_pk_bf16_f32 v95, v96, v97
	v_cvt_pk_bf16_f32 v96, v90, v91
	v_cvt_pk_bf16_f32 v93, v92, v93
	s_nop 1
	ds_bpermute_b32 v90, v132, v94
	ds_bpermute_b32 v91, v132, v95
	ds_bpermute_b32 v92, v132, v96
	ds_bpermute_b32 v93, v132, v93
	s_waitcnt lgkmcnt(0)
	global_store_dwordx4 v[134:135], v[90:93], off
	s_waitcnt vmcnt(15)
	ds_bpermute_b32 v143, v133, v167
	ds_bpermute_b32 v142, v133, v166
	ds_bpermute_b32 v145, v133, v169
	ds_bpermute_b32 v144, v133, v168
	s_waitcnt lgkmcnt(3)
	v_lshlrev_b32_e32 v136, 16, v143
	v_and_b32_e32 v137, 0xffff0000, v143
	s_waitcnt lgkmcnt(2)
	v_and_b32_e32 v143, 0xffff0000, v142
	v_lshlrev_b32_e32 v142, 16, v142
	v_pk_mul_f32 v[136:137], v[136:137], s[96:97] op_sel_hi:[1,0]
	v_pk_fma_f32 v[88:89], v[88:89], 0.5, v[136:137] op_sel_hi:[1,0,1]
	v_pk_mul_f32 v[142:143], v[142:143], s[96:97] op_sel_hi:[1,0]
	v_pk_fma_f32 v[86:87], v[86:87], 0.5, v[142:143] op_sel_hi:[1,0,1]
	s_waitcnt lgkmcnt(1)
	v_lshlrev_b32_e32 v136, 16, v145
	v_and_b32_e32 v137, 0xffff0000, v145
	s_waitcnt lgkmcnt(0)
	v_and_b32_e32 v145, 0xffff0000, v144
	v_lshlrev_b32_e32 v144, 16, v144
	v_pk_mul_f32 v[136:137], v[136:137], s[96:97] op_sel_hi:[1,0]
	v_pk_fma_f32 v[84:85], v[84:85], 0.5, v[136:137] op_sel_hi:[1,0,1]
	v_pk_mul_f32 v[144:145], v[144:145], s[96:97] op_sel_hi:[1,0]
	v_pk_fma_f32 v[82:83], v[82:83], 0.5, v[144:145] op_sel_hi:[1,0,1]
	v_cvt_pk_bf16_f32 v86, v86, v87
	v_cvt_pk_bf16_f32 v87, v88, v89
	v_cvt_pk_bf16_f32 v88, v82, v83
	v_cvt_pk_bf16_f32 v85, v84, v85
	s_nop 1
	ds_bpermute_b32 v82, v132, v86
	ds_bpermute_b32 v83, v132, v87
	ds_bpermute_b32 v84, v132, v88
	ds_bpermute_b32 v85, v132, v85
	s_waitcnt lgkmcnt(0)
; #define GAS __attribute__((address_space(1)))
; __device__ __forceinline__ v4u tr4(int a, v4u x) { return (v4u){bperm(a, x.x), bperm(a, x.y), bperm(a, x.z), bperm(a, x.w)}; }
; __device__ __forceinline__ v4u pack8(const f32x4& a, const f32x4& b) { return (v4u){pg8::cvt_pk_bf16(a[0], a[1]), pg8::cvt_pk_bf16(a[2], a[3]), pg8::cvt_pk_bf16(b[0], b[1]), pg8::cvt_pk_bf16(b[2], b[3])}; }
;     __device__ __forceinline__ bool operator()(AccT& acc, const Unit& u, int wr, int wc, int fr, int fq) const {
;     ...
;             for (int m = 0; m < 4; ++m) { const size_t off = (size_t)(row0 + ai * 128 + m * 16) * D + col0;
; #pragma unroll
;                 for (int bj = 0; bj < 2; ++bj) { const v4u r = tr4(t.push, *(const GAS v4u*)(src + off + bj * 128));
;                     const f32x4 y0 = (f32x4){bflo(r.x), bfhi(r.x), bflo(r.y), bfhi(r.y)} * ca + acc[ai][bj][m][0] * cb, y1 = (f32x4){bflo(r.z), bfhi(r.z), bflo(r.w), bfhi(r.w)} * ca + acc[ai][bj][m][1] * cb;
;                     *(GAS v4u*)(dst + off + bj * 128) = tr4(t.pull, pack8(y0, y1)); } }
	global_store_dwordx4 v[134:135], v[82:85], off offset:256
	s_waitcnt vmcnt(15)
	ds_bpermute_b32 v143, v133, v171
	ds_bpermute_b32 v142, v133, v170
	ds_bpermute_b32 v145, v133, v173
	ds_bpermute_b32 v144, v133, v172
	s_mov_b64 s[12:13], 0x18000
	v_lshl_add_u64 v[134:135], v[140:141], 0, s[12:13]
	s_waitcnt lgkmcnt(3)
	v_lshlrev_b32_e32 v136, 16, v143
	v_and_b32_e32 v137, 0xffff0000, v143
	s_waitcnt lgkmcnt(2)
	v_and_b32_e32 v143, 0xffff0000, v142
	v_lshlrev_b32_e32 v142, 16, v142
	v_pk_mul_f32 v[136:137], v[136:137], s[96:97] op_sel_hi:[1,0]
	v_pk_fma_f32 v[80:81], v[80:81], 0.5, v[136:137] op_sel_hi:[1,0,1]
	v_pk_mul_f32 v[142:143], v[142:143], s[96:97] op_sel_hi:[1,0]
	v_pk_fma_f32 v[78:79], v[78:79], 0.5, v[142:143] op_sel_hi:[1,0,1]
	s_waitcnt lgkmcnt(1)
	v_lshlrev_b32_e32 v136, 16, v145
	v_and_b32_e32 v137, 0xffff0000, v145
	s_waitcnt lgkmcnt(0)
	v_and_b32_e32 v145, 0xffff0000, v144
	v_lshlrev_b32_e32 v144, 16, v144
	v_pk_mul_f32 v[136:137], v[136:137], s[96:97] op_sel_hi:[1,0]
	v_pk_fma_f32 v[76:77], v[76:77], 0.5, v[136:137] op_sel_hi:[1,0,1]
	v_pk_mul_f32 v[144:145], v[144:145], s[96:97] op_sel_hi:[1,0]
	v_pk_fma_f32 v[74:75], v[74:75], 0.5, v[144:145] op_sel_hi:[1,0,1]
	v_cvt_pk_bf16_f32 v78, v78, v79
	v_cvt_pk_bf16_f32 v79, v80, v81
	v_cvt_pk_bf16_f32 v80, v74, v75
	v_cvt_pk_bf16_f32 v77, v76, v77
	s_nop 1
	ds_bpermute_b32 v74, v132, v78
	ds_bpermute_b32 v75, v132, v79
	ds_bpermute_b32 v76, v132, v80
	ds_bpermute_b32 v77, v132, v77
	s_waitcnt lgkmcnt(0)
	global_store_dwordx4 v[134:135], v[74:77], off
	s_waitcnt vmcnt(15)
	ds_bpermute_b32 v143, v133, v175
	ds_bpermute_b32 v142, v133, v174
	ds_bpermute_b32 v145, v133, v177
	ds_bpermute_b32 v144, v133, v176
	s_waitcnt lgkmcnt(3)
	v_lshlrev_b32_e32 v136, 16, v143
	v_and_b32_e32 v137, 0xffff0000, v143
	s_waitcnt lgkmcnt(2)
	v_and_b32_e32 v143, 0xffff0000, v142
	v_lshlrev_b32_e32 v142, 16, v142
	v_pk_mul_f32 v[136:137], v[136:137], s[96:97] op_sel_hi:[1,0]
	v_pk_fma_f32 v[72:73], v[72:73], 0.5, v[136:137] op_sel_hi:[1,0,1]
	v_pk_mul_f32 v[142:143], v[142:143], s[96:97] op_sel_hi:[1,0]
	v_pk_fma_f32 v[70:71], v[70:71], 0.5, v[142:143] op_sel_hi:[1,0,1]
	s_waitcnt lgkmcnt(1)
	v_lshlrev_b32_e32 v136, 16, v145
	v_and_b32_e32 v137, 0xffff0000, v145
	s_waitcnt lgkmcnt(0)
	v_and_b32_e32 v145, 0xffff0000, v144
	v_lshlrev_b32_e32 v144, 16, v144
	v_pk_mul_f32 v[136:137], v[136:137], s[96:97] op_sel_hi:[1,0]
	v_pk_fma_f32 v[68:69], v[68:69], 0.5, v[136:137] op_sel_hi:[1,0,1]
	v_pk_mul_f32 v[144:145], v[144:145], s[96:97] op_sel_hi:[1,0]
	v_pk_fma_f32 v[66:67], v[66:67], 0.5, v[144:145] op_sel_hi:[1,0,1]
	v_cvt_pk_bf16_f32 v70, v70, v71
	v_cvt_pk_bf16_f32 v71, v72, v73
	v_cvt_pk_bf16_f32 v72, v66, v67
	v_cvt_pk_bf16_f32 v69, v68, v69
	s_nop 1
	ds_bpermute_b32 v66, v132, v70
	ds_bpermute_b32 v67, v132, v71
	ds_bpermute_b32 v68, v132, v72
	ds_bpermute_b32 v69, v132, v69
	s_waitcnt lgkmcnt(0)
	global_store_dwordx4 v[134:135], v[66:69], off offset:256
	s_waitcnt vmcnt(15)
	ds_bpermute_b32 v143, v133, v179
	ds_bpermute_b32 v142, v133, v178
	ds_bpermute_b32 v145, v133, v181
	ds_bpermute_b32 v144, v133, v180
	s_mov_b64 s[12:13], 0x40000
	v_lshl_add_u64 v[134:135], v[140:141], 0, s[12:13]
	s_waitcnt lgkmcnt(3)
	v_lshlrev_b32_e32 v136, 16, v143
	v_and_b32_e32 v137, 0xffff0000, v143
	s_waitcnt lgkmcnt(2)
	v_and_b32_e32 v143, 0xffff0000, v142
	v_lshlrev_b32_e32 v142, 16, v142
	v_pk_mul_f32 v[136:137], v[136:137], s[96:97] op_sel_hi:[1,0]
	v_pk_fma_f32 v[64:65], v[64:65], 0.5, v[136:137] op_sel_hi:[1,0,1]
	v_pk_mul_f32 v[142:143], v[142:143], s[96:97] op_sel_hi:[1,0]
	v_pk_fma_f32 v[62:63], v[62:63], 0.5, v[142:143] op_sel_hi:[1,0,1]
	s_waitcnt lgkmcnt(1)
	v_lshlrev_b32_e32 v136, 16, v145
	v_and_b32_e32 v137, 0xffff0000, v145
	s_waitcnt lgkmcnt(0)
	v_and_b32_e32 v145, 0xffff0000, v144
	v_lshlrev_b32_e32 v144, 16, v144
	v_pk_mul_f32 v[136:137], v[136:137], s[96:97] op_sel_hi:[1,0]
	v_pk_fma_f32 v[60:61], v[60:61], 0.5, v[136:137] op_sel_hi:[1,0,1]
	v_pk_mul_f32 v[144:145], v[144:145], s[96:97] op_sel_hi:[1,0]
	v_pk_fma_f32 v[58:59], v[58:59], 0.5, v[144:145] op_sel_hi:[1,0,1]
	v_cvt_pk_bf16_f32 v62, v62, v63
	v_cvt_pk_bf16_f32 v63, v64, v65
	v_cvt_pk_bf16_f32 v64, v58, v59
	v_cvt_pk_bf16_f32 v61, v60, v61
	s_nop 1
	ds_bpermute_b32 v58, v132, v62
	ds_bpermute_b32 v59, v132, v63
	ds_bpermute_b32 v60, v132, v64
	ds_bpermute_b32 v61, v132, v61
	s_waitcnt lgkmcnt(0)
	global_store_dwordx4 v[134:135], v[58:61], off
	s_waitcnt vmcnt(15)
	ds_bpermute_b32 v143, v133, v183
	ds_bpermute_b32 v142, v133, v182
	ds_bpermute_b32 v145, v133, v185
	ds_bpermute_b32 v144, v133, v184
	s_waitcnt lgkmcnt(3)
	v_lshlrev_b32_e32 v136, 16, v143
	v_and_b32_e32 v137, 0xffff0000, v143
	s_waitcnt lgkmcnt(2)
	v_and_b32_e32 v143, 0xffff0000, v142
	v_lshlrev_b32_e32 v142, 16, v142
	v_pk_mul_f32 v[136:137], v[136:137], s[96:97] op_sel_hi:[1,0]
	v_pk_fma_f32 v[56:57], v[56:57], 0.5, v[136:137] op_sel_hi:[1,0,1]
	v_pk_mul_f32 v[142:143], v[142:143], s[96:97] op_sel_hi:[1,0]
	v_pk_fma_f32 v[54:55], v[54:55], 0.5, v[142:143] op_sel_hi:[1,0,1]
	s_waitcnt lgkmcnt(1)
	v_lshlrev_b32_e32 v136, 16, v145
	v_and_b32_e32 v137, 0xffff0000, v145
	s_waitcnt lgkmcnt(0)
	v_and_b32_e32 v145, 0xffff0000, v144
	v_lshlrev_b32_e32 v144, 16, v144
	v_pk_mul_f32 v[136:137], v[136:137], s[96:97] op_sel_hi:[1,0]
	v_pk_fma_f32 v[52:53], v[52:53], 0.5, v[136:137] op_sel_hi:[1,0,1]
	v_pk_mul_f32 v[144:145], v[144:145], s[96:97] op_sel_hi:[1,0]
	v_pk_fma_f32 v[50:51], v[50:51], 0.5, v[144:145] op_sel_hi:[1,0,1]
	v_cvt_pk_bf16_f32 v54, v54, v55
	v_cvt_pk_bf16_f32 v55, v56, v57
	v_cvt_pk_bf16_f32 v56, v50, v51
	v_cvt_pk_bf16_f32 v53, v52, v53
	s_nop 1
	ds_bpermute_b32 v50, v132, v54
	ds_bpermute_b32 v51, v132, v55
	ds_bpermute_b32 v52, v132, v56
	ds_bpermute_b32 v53, v132, v53
	s_waitcnt lgkmcnt(0)
; #define GAS __attribute__((address_space(1)))
; __device__ __forceinline__ v4u tr4(int a, v4u x) { return (v4u){bperm(a, x.x), bperm(a, x.y), bperm(a, x.z), bperm(a, x.w)}; }
; __device__ __forceinline__ v4u pack8(const f32x4& a, const f32x4& b) { return (v4u){pg8::cvt_pk_bf16(a[0], a[1]), pg8::cvt_pk_bf16(a[2], a[3]), pg8::cvt_pk_bf16(b[0], b[1]), pg8::cvt_pk_bf16(b[2], b[3])}; }
;     __device__ __forceinline__ bool operator()(AccT& acc, const Unit& u, int wr, int wc, int fr, int fq) const {
;     ...
;             for (int m = 0; m < 4; ++m) { const size_t off = (size_t)(row0 + ai * 128 + m * 16) * D + col0;
; #pragma unroll
;                 for (int bj = 0; bj < 2; ++bj) { const v4u r = tr4(t.push, *(const GAS v4u*)(src + off + bj * 128));
;                     const f32x4 y0 = (f32x4){bflo(r.x), bfhi(r.x), bflo(r.y), bfhi(r.y)} * ca + acc[ai][bj][m][0] * cb, y1 = (f32x4){bflo(r.z), bfhi(r.z), bflo(r.w), bfhi(r.w)} * ca + acc[ai][bj][m][1] * cb;
;                     *(GAS v4u*)(dst + off + bj * 128) = tr4(t.pull, pack8(y0, y1)); } }
	global_store_dwordx4 v[134:135], v[50:53], off offset:256
	s_waitcnt vmcnt(15)
	ds_bpermute_b32 v143, v133, v187
	ds_bpermute_b32 v142, v133, v186
	ds_bpermute_b32 v145, v133, v189
	ds_bpermute_b32 v144, v133, v188
	s_mov_b64 s[12:13], 0x48000
	v_lshl_add_u64 v[134:135], v[140:141], 0, s[12:13]
	s_waitcnt lgkmcnt(3)
	v_lshlrev_b32_e32 v136, 16, v143
	v_and_b32_e32 v137, 0xffff0000, v143
	s_waitcnt lgkmcnt(2)
	v_and_b32_e32 v143, 0xffff0000, v142
	v_lshlrev_b32_e32 v142, 16, v142
	v_pk_mul_f32 v[136:137], v[136:137], s[96:97] op_sel_hi:[1,0]
	v_pk_fma_f32 v[48:49], v[48:49], 0.5, v[136:137] op_sel_hi:[1,0,1]
	v_pk_mul_f32 v[142:143], v[142:143], s[96:97] op_sel_hi:[1,0]
	v_pk_fma_f32 v[46:47], v[46:47], 0.5, v[142:143] op_sel_hi:[1,0,1]
	s_waitcnt lgkmcnt(1)
	v_lshlrev_b32_e32 v136, 16, v145
	v_and_b32_e32 v137, 0xffff0000, v145
	s_waitcnt lgkmcnt(0)
	v_and_b32_e32 v145, 0xffff0000, v144
	v_lshlrev_b32_e32 v144, 16, v144
	v_pk_mul_f32 v[136:137], v[136:137], s[96:97] op_sel_hi:[1,0]
	v_pk_fma_f32 v[44:45], v[44:45], 0.5, v[136:137] op_sel_hi:[1,0,1]
	v_pk_mul_f32 v[144:145], v[144:145], s[96:97] op_sel_hi:[1,0]
	v_pk_fma_f32 v[42:43], v[42:43], 0.5, v[144:145] op_sel_hi:[1,0,1]
	v_cvt_pk_bf16_f32 v46, v46, v47
	v_cvt_pk_bf16_f32 v47, v48, v49
	v_cvt_pk_bf16_f32 v48, v42, v43
	v_cvt_pk_bf16_f32 v45, v44, v45
	s_nop 1
	ds_bpermute_b32 v42, v132, v46
	ds_bpermute_b32 v43, v132, v47
	ds_bpermute_b32 v44, v132, v48
	ds_bpermute_b32 v45, v132, v45
	s_waitcnt lgkmcnt(0)
	global_store_dwordx4 v[134:135], v[42:45], off
	s_waitcnt vmcnt(15)
	ds_bpermute_b32 v143, v133, v191
	ds_bpermute_b32 v142, v133, v190
	ds_bpermute_b32 v145, v133, v193
	ds_bpermute_b32 v144, v133, v192
	s_waitcnt lgkmcnt(3)
	v_lshlrev_b32_e32 v136, 16, v143
	v_and_b32_e32 v137, 0xffff0000, v143
	s_waitcnt lgkmcnt(2)
	v_and_b32_e32 v143, 0xffff0000, v142
	v_lshlrev_b32_e32 v142, 16, v142
	v_pk_mul_f32 v[136:137], v[136:137], s[96:97] op_sel_hi:[1,0]
	v_pk_fma_f32 v[40:41], v[40:41], 0.5, v[136:137] op_sel_hi:[1,0,1]
	v_pk_mul_f32 v[142:143], v[142:143], s[96:97] op_sel_hi:[1,0]
	v_pk_fma_f32 v[38:39], v[38:39], 0.5, v[142:143] op_sel_hi:[1,0,1]
	s_waitcnt lgkmcnt(1)
	v_lshlrev_b32_e32 v136, 16, v145
	v_and_b32_e32 v137, 0xffff0000, v145
	s_waitcnt lgkmcnt(0)
	v_and_b32_e32 v145, 0xffff0000, v144
	v_lshlrev_b32_e32 v144, 16, v144
	v_pk_mul_f32 v[136:137], v[136:137], s[96:97] op_sel_hi:[1,0]
	v_pk_fma_f32 v[36:37], v[36:37], 0.5, v[136:137] op_sel_hi:[1,0,1]
	v_pk_mul_f32 v[144:145], v[144:145], s[96:97] op_sel_hi:[1,0]
	v_pk_fma_f32 v[34:35], v[34:35], 0.5, v[144:145] op_sel_hi:[1,0,1]
	v_cvt_pk_bf16_f32 v38, v38, v39
	v_cvt_pk_bf16_f32 v39, v40, v41
	v_cvt_pk_bf16_f32 v40, v34, v35
	v_cvt_pk_bf16_f32 v37, v36, v37
	s_nop 1
	ds_bpermute_b32 v34, v132, v38
	ds_bpermute_b32 v35, v132, v39
	ds_bpermute_b32 v36, v132, v40
	ds_bpermute_b32 v37, v132, v37
	s_waitcnt lgkmcnt(0)
	global_store_dwordx4 v[134:135], v[34:37], off offset:256
	s_waitcnt vmcnt(14)
	ds_bpermute_b32 v143, v133, v127
	ds_bpermute_b32 v142, v133, v126
	ds_bpermute_b32 v145, v133, v129
	ds_bpermute_b32 v144, v133, v128
	s_mov_b64 s[12:13], 0x50000
	v_lshl_add_u64 v[134:135], v[140:141], 0, s[12:13]
	s_waitcnt lgkmcnt(3)
	v_lshlrev_b32_e32 v136, 16, v143
	v_and_b32_e32 v137, 0xffff0000, v143
	s_waitcnt lgkmcnt(2)
	v_and_b32_e32 v143, 0xffff0000, v142
	v_lshlrev_b32_e32 v142, 16, v142
	v_pk_mul_f32 v[136:137], v[136:137], s[96:97] op_sel_hi:[1,0]
	v_pk_fma_f32 v[32:33], v[32:33], 0.5, v[136:137] op_sel_hi:[1,0,1]
	v_pk_mul_f32 v[142:143], v[142:143], s[96:97] op_sel_hi:[1,0]
	v_pk_fma_f32 v[30:31], v[30:31], 0.5, v[142:143] op_sel_hi:[1,0,1]
	s_waitcnt lgkmcnt(1)
	v_lshlrev_b32_e32 v136, 16, v145
	v_and_b32_e32 v137, 0xffff0000, v145
	s_waitcnt lgkmcnt(0)
	v_and_b32_e32 v145, 0xffff0000, v144
	v_lshlrev_b32_e32 v144, 16, v144
	v_pk_mul_f32 v[136:137], v[136:137], s[96:97] op_sel_hi:[1,0]
	v_pk_fma_f32 v[28:29], v[28:29], 0.5, v[136:137] op_sel_hi:[1,0,1]
	v_pk_mul_f32 v[144:145], v[144:145], s[96:97] op_sel_hi:[1,0]
	v_pk_fma_f32 v[26:27], v[26:27], 0.5, v[144:145] op_sel_hi:[1,0,1]
	v_cvt_pk_bf16_f32 v30, v30, v31
	v_cvt_pk_bf16_f32 v31, v32, v33
	v_cvt_pk_bf16_f32 v32, v26, v27
	v_cvt_pk_bf16_f32 v29, v28, v29
	s_nop 1
	ds_bpermute_b32 v26, v132, v30
	ds_bpermute_b32 v27, v132, v31
	ds_bpermute_b32 v28, v132, v32
	ds_bpermute_b32 v29, v132, v29
	s_waitcnt lgkmcnt(0)
	global_store_dwordx4 v[134:135], v[26:29], off
	s_waitcnt vmcnt(13)
; #define GAS __attribute__((address_space(1)))
; __device__ __forceinline__ v4u tr4(int a, v4u x) { return (v4u){bperm(a, x.x), bperm(a, x.y), bperm(a, x.z), bperm(a, x.w)}; }
; __device__ __forceinline__ v4u pack8(const f32x4& a, const f32x4& b) { return (v4u){pg8::cvt_pk_bf16(a[0], a[1]), pg8::cvt_pk_bf16(a[2], a[3]), pg8::cvt_pk_bf16(b[0], b[1]), pg8::cvt_pk_bf16(b[2], b[3])}; }
;     __device__ __forceinline__ bool operator()(AccT& acc, const Unit& u, int wr, int wc, int fr, int fq) const {
;     ...
;             for (int m = 0; m < 4; ++m) { const size_t off = (size_t)(row0 + ai * 128 + m * 16) * D + col0;
; #pragma unroll
;                 for (int bj = 0; bj < 2; ++bj) { const v4u r = tr4(t.push, *(const GAS v4u*)(src + off + bj * 128));
;                     const f32x4 y0 = (f32x4){bflo(r.x), bfhi(r.x), bflo(r.y), bfhi(r.y)} * ca + acc[ai][bj][m][0] * cb, y1 = (f32x4){bflo(r.z), bfhi(r.z), bflo(r.w), bfhi(r.w)} * ca + acc[ai][bj][m][1] * cb;
;                     *(GAS v4u*)(dst + off + bj * 128) = tr4(t.pull, pack8(y0, y1)); } }
	ds_bpermute_b32 v143, v133, v119
	ds_bpermute_b32 v142, v133, v118
	ds_bpermute_b32 v145, v133, v121
	ds_bpermute_b32 v144, v133, v120
	s_waitcnt lgkmcnt(3)
	v_lshlrev_b32_e32 v136, 16, v143
	v_and_b32_e32 v137, 0xffff0000, v143
	s_waitcnt lgkmcnt(2)
	v_and_b32_e32 v143, 0xffff0000, v142
	v_lshlrev_b32_e32 v142, 16, v142
	v_pk_mul_f32 v[136:137], v[136:137], s[96:97] op_sel_hi:[1,0]
	v_pk_fma_f32 v[24:25], v[24:25], 0.5, v[136:137] op_sel_hi:[1,0,1]
	v_pk_mul_f32 v[142:143], v[142:143], s[96:97] op_sel_hi:[1,0]
	v_pk_fma_f32 v[22:23], v[22:23], 0.5, v[142:143] op_sel_hi:[1,0,1]
	s_waitcnt lgkmcnt(1)
	v_lshlrev_b32_e32 v136, 16, v145
	v_and_b32_e32 v137, 0xffff0000, v145
	s_waitcnt lgkmcnt(0)
	v_and_b32_e32 v145, 0xffff0000, v144
	v_lshlrev_b32_e32 v144, 16, v144
	v_pk_mul_f32 v[136:137], v[136:137], s[96:97] op_sel_hi:[1,0]
	v_pk_fma_f32 v[20:21], v[20:21], 0.5, v[136:137] op_sel_hi:[1,0,1]
	v_pk_mul_f32 v[144:145], v[144:145], s[96:97] op_sel_hi:[1,0]
	v_pk_fma_f32 v[18:19], v[18:19], 0.5, v[144:145] op_sel_hi:[1,0,1]
	v_cvt_pk_bf16_f32 v22, v22, v23
	v_cvt_pk_bf16_f32 v23, v24, v25
	v_cvt_pk_bf16_f32 v24, v18, v19
	v_cvt_pk_bf16_f32 v21, v20, v21
	s_nop 1
	ds_bpermute_b32 v18, v132, v22
	ds_bpermute_b32 v19, v132, v23
	ds_bpermute_b32 v20, v132, v24
	ds_bpermute_b32 v21, v132, v21
	s_waitcnt lgkmcnt(0)
	global_store_dwordx4 v[134:135], v[18:21], off offset:256
	s_waitcnt vmcnt(12)
	ds_bpermute_b32 v143, v133, v111
	ds_bpermute_b32 v142, v133, v110
	ds_bpermute_b32 v145, v133, v113
	ds_bpermute_b32 v144, v133, v112
	s_mov_b64 s[12:13], 0x58000
	v_lshl_add_u64 v[134:135], v[140:141], 0, s[12:13]
	s_waitcnt lgkmcnt(3)
	v_lshlrev_b32_e32 v136, 16, v143
	v_and_b32_e32 v137, 0xffff0000, v143
	s_waitcnt lgkmcnt(2)
	v_and_b32_e32 v143, 0xffff0000, v142
	v_lshlrev_b32_e32 v142, 16, v142
	v_pk_mul_f32 v[136:137], v[136:137], s[96:97] op_sel_hi:[1,0]
	v_pk_fma_f32 v[16:17], v[16:17], 0.5, v[136:137] op_sel_hi:[1,0,1]
	v_pk_mul_f32 v[142:143], v[142:143], s[96:97] op_sel_hi:[1,0]
	v_pk_fma_f32 v[14:15], v[14:15], 0.5, v[142:143] op_sel_hi:[1,0,1]
	s_waitcnt lgkmcnt(1)
	v_lshlrev_b32_e32 v136, 16, v145
	v_and_b32_e32 v137, 0xffff0000, v145
	s_waitcnt lgkmcnt(0)
	v_and_b32_e32 v145, 0xffff0000, v144
	v_lshlrev_b32_e32 v144, 16, v144
	v_pk_mul_f32 v[136:137], v[136:137], s[96:97] op_sel_hi:[1,0]
	v_pk_fma_f32 v[12:13], v[12:13], 0.5, v[136:137] op_sel_hi:[1,0,1]
	v_pk_mul_f32 v[144:145], v[144:145], s[96:97] op_sel_hi:[1,0]
	v_pk_fma_f32 v[10:11], v[10:11], 0.5, v[144:145] op_sel_hi:[1,0,1]
	v_cvt_pk_bf16_f32 v14, v14, v15
	v_cvt_pk_bf16_f32 v15, v16, v17
	v_cvt_pk_bf16_f32 v16, v10, v11
	v_cvt_pk_bf16_f32 v13, v12, v13
	s_nop 1
	ds_bpermute_b32 v10, v132, v14
	ds_bpermute_b32 v11, v132, v15
	ds_bpermute_b32 v12, v132, v16
	ds_bpermute_b32 v13, v132, v13
	s_waitcnt lgkmcnt(0)
	global_store_dwordx4 v[134:135], v[10:13], off
	s_waitcnt vmcnt(11)
	ds_bpermute_b32 v143, v133, v103
	ds_bpermute_b32 v142, v133, v102
	ds_bpermute_b32 v145, v133, v105
	ds_bpermute_b32 v144, v133, v104
	s_waitcnt lgkmcnt(3)
	v_lshlrev_b32_e32 v136, 16, v143
	v_and_b32_e32 v137, 0xffff0000, v143
	s_waitcnt lgkmcnt(2)
	v_and_b32_e32 v143, 0xffff0000, v142
	v_lshlrev_b32_e32 v142, 16, v142
	v_pk_mul_f32 v[136:137], v[136:137], s[96:97] op_sel_hi:[1,0]
	v_pk_fma_f32 v[8:9], v[8:9], 0.5, v[136:137] op_sel_hi:[1,0,1]
	v_pk_mul_f32 v[142:143], v[142:143], s[96:97] op_sel_hi:[1,0]
	v_pk_fma_f32 v[6:7], v[6:7], 0.5, v[142:143] op_sel_hi:[1,0,1]
	s_waitcnt lgkmcnt(1)
	v_lshlrev_b32_e32 v136, 16, v145
	v_and_b32_e32 v137, 0xffff0000, v145
	s_waitcnt lgkmcnt(0)
	v_and_b32_e32 v145, 0xffff0000, v144
	v_lshlrev_b32_e32 v144, 16, v144
	v_pk_mul_f32 v[136:137], v[136:137], s[96:97] op_sel_hi:[1,0]
	v_pk_fma_f32 v[4:5], v[4:5], 0.5, v[136:137] op_sel_hi:[1,0,1]
	v_pk_mul_f32 v[144:145], v[144:145], s[96:97] op_sel_hi:[1,0]
	v_pk_fma_f32 v[2:3], v[2:3], 0.5, v[144:145] op_sel_hi:[1,0,1]
	v_cvt_pk_bf16_f32 v6, v6, v7
	v_cvt_pk_bf16_f32 v7, v8, v9
	v_cvt_pk_bf16_f32 v8, v2, v3
	v_cvt_pk_bf16_f32 v5, v4, v5
	s_nop 1
	ds_bpermute_b32 v2, v132, v6
	ds_bpermute_b32 v3, v132, v7
	ds_bpermute_b32 v4, v132, v8
	ds_bpermute_b32 v5, v132, v5
	s_waitcnt lgkmcnt(0)
	global_store_dwordx4 v[134:135], v[2:5], off offset:256
	s_mov_b64 s[12:13], -1
	s_cbranch_vccnz .LBB0_2018
	s_andn2_b64 vcc, exec, s[2:3]
	s_cbranch_vccnz .LBB0_2017
	s_barrier
	s_branch .LBB0_2017
